# hyena tasks: boundary-element ushort loads de-serialised (all loads of a group in flight, one wait)
# speedup vs baseline: 1.0462x; 1.0016x over previous
.LBB0_380:
	s_or_b64 exec, exec, s[0:1]
	v_cmp_gt_i32_e32 vcc, 33, v41
	v_add_u32_e32 v64, 0x200, v41
	s_and_saveexec_b64 s[0:1], vcc
	v_cmp_ne_u32_e32 vcc, 32, v41
	s_nop 1
	v_cndmask_b32_e32 v0, 0, v64, vcc
	v_lshlrev_b32_e32 v0, 1, v0
	ds_write_b16 v0, v1
	s_or_b64 exec, exec, s[0:1]
	s_lshl_b64 s[0:1], s[50:51], 2
	s_add_u32 s4, s86, s0
	s_addc_u32 s5, s87, s1
	s_add_u32 s0, s90, s0
	s_addc_u32 s1, s78, s1
	v_mov_b32_e32 v0, 0x1000
	v_mov_b32_e32 v2, 0x2000
	s_or_b32 s6, s50, 0x200
	global_load_dword v21, v1, s[4:5] offset:1024
	global_load_dword v20, v0, s[4:5]
	global_load_dword v12, v0, s[4:5] offset:3072
	global_load_dword v19, v1, s[4:5] offset:2048
	global_load_dword v18, v0, s[4:5] offset:1024
	global_load_dword v10, v2, s[4:5]
	global_load_dword v39, v1, s[4:5]
	s_nop 0
	global_load_dword v0, v0, s[4:5] offset:2048
	s_nop 0
	global_load_dword v16, v1, s[0:1] offset:1024
	global_load_dword v14, v1, s[0:1] offset:2048
	global_load_dword v38, v1, s[4:5] offset:3072
	global_load_dword v40, v1, s[0:1]
	s_mul_i32 s1, s28, 0xc000
	v_readlane_b32 s4, v253, 40
	s_mul_hi_u32 s0, s28, 0xc000
	s_add_u32 s28, s4, s1
	v_readlane_b32 s1, v253, 41
	s_addc_u32 s29, s1, s0
	s_mul_hi_u32 s0, s6, 0xc000
	s_mul_i32 s6, s6, 0xc000
	s_add_u32 s38, s4, s6
	v_lshlrev_b64 v[44:45], 1, v[42:43]
	s_addc_u32 s39, s1, s0
	s_waitcnt vmcnt(22)
	v_lshl_add_u64 v[24:25], s[28:29], 0, v[44:45]
	s_waitcnt vmcnt(21)
	v_lshl_add_u64 v[28:29], s[38:39], 0, v[44:45]
	global_load_dwordx4 v[6:9], v[24:25], off
	global_load_dwordx4 v[2:5], v[28:29], off
	v_ashrrev_i32_e32 v11, 31, v41
	v_lshrrev_b32_e32 v43, 27, v11
	v_add_u32_e32 v11, v41, v43
	v_ashrrev_i32_e32 v60, 5, v11
	v_lshlrev_b32_e32 v11, 8, v60
	v_sub_u32_e32 v62, v42, v11
	v_cmp_lt_i32_e32 vcc, 0, v62
	v_mov_b32_e32 v23, 0
	v_mov_b32_e32 v27, 0
	s_and_saveexec_b64 s[0:1], vcc
	s_cbranch_execz .LBB0_384
	global_load_ushort v27, v[24:25], off offset:-2
.LBB0_384:
	s_or_b64 exec, exec, s[0:1]
	s_movk_i32 s0, 0xf8
	v_cmp_gt_i32_e64 s[0:1], s0, v62
	s_and_saveexec_b64 s[40:41], s[0:1]
	s_cbranch_execz .LBB0_386
	global_load_ushort v23, v[24:25], off offset:16
.LBB0_386:
	s_or_b64 exec, exec, s[40:41]
	v_mov_b32_e32 v25, 0
	s_waitcnt vmcnt(22)
	v_mov_b32_e32 v31, 0
	s_and_saveexec_b64 s[40:41], vcc
	s_cbranch_execz .LBB0_388
	global_load_ushort v31, v[28:29], off offset:-2
.LBB0_388:
	s_or_b64 exec, exec, s[40:41]
	s_and_saveexec_b64 s[40:41], s[0:1]
	s_cbranch_execz .LBB0_390
	global_load_ushort v25, v[28:29], off offset:16
.LBB0_390:
	s_or_b64 exec, exec, s[40:41]
	s_waitcnt vmcnt(0)
	v_lshlrev_b32_e32 v27, 16, v27
	v_lshlrev_b32_e32 v23, 16, v23
	v_lshlrev_b32_e32 v31, 16, v31
	v_lshlrev_b32_e32 v25, 16, v25
	v_lshlrev_b32_e32 v22, 16, v6
	v_lshlrev_b32_e32 v29, 16, v9
	v_and_b32_e32 v33, 0xffff0000, v9
	s_waitcnt vmcnt(0)
	v_and_b32_e32 v34, 0xffff0000, v4
	v_lshlrev_b32_e32 v9, 16, v4
	v_and_b32_e32 v4, 0xffff0000, v6
	v_and_b32_e32 v6, 0xffff0000, v2
	v_mov_b32_e32 v26, v4
	v_mov_b32_e32 v30, v6
	v_lshlrev_b32_e32 v24, 16, v2
	v_and_b32_e32 v28, 0xffff0000, v8
	v_lshlrev_b32_e32 v35, 16, v5
	v_and_b32_e32 v37, 0xffff0000, v5
	v_and_b32_e32 v46, 0xffff0000, v7
	v_lshlrev_b32_e32 v47, 16, v8
	v_and_b32_e32 v8, 0xffff0000, v3
	v_lshlrev_b32_e32 v5, 16, v7
	v_lshlrev_b32_e32 v7, 16, v3
	v_pk_mul_f32 v[2:3], v[20:21], v[26:27]
	v_pk_mul_f32 v[26:27], v[18:19], v[30:31]
	v_pk_fma_f32 v[2:3], v[20:21], v[22:23], v[2:3] op_sel:[0,0,1] op_sel_hi:[1,0,0]
	v_pk_fma_f32 v[26:27], v[18:19], v[24:25], v[26:27] op_sel:[0,0,1] op_sel_hi:[1,0,0]
	v_pk_fma_f32 v[2:3], v[12:13], v[4:5], v[2:3] op_sel_hi:[0,1,1]
	v_pk_fma_f32 v[26:27], v[10:11], v[6:7], v[26:27] op_sel_hi:[0,1,1]
	v_pk_add_f32 v[2:3], v[16:17], v[2:3] op_sel_hi:[0,1]
	v_pk_add_f32 v[26:27], v[14:15], v[26:27] op_sel_hi:[0,1]
	v_pk_mul_f32 v[2:3], v[2:3], v[26:27]
	v_pk_mov_b32 v[26:27], v[4:5], v[46:47] op_sel:[1,0]
	v_mov_b32_e32 v22, v21
	v_pk_mul_f32 v[26:27], v[20:21], v[26:27] op_sel_hi:[0,1]
	v_pk_fma_f32 v[4:5], v[22:23], v[4:5], v[26:27] op_sel_hi:[0,1,1]
	v_pk_mov_b32 v[26:27], v[6:7], v[8:9] op_sel:[1,0]
	v_mov_b32_e32 v24, v19
	v_pk_mul_f32 v[26:27], v[18:19], v[26:27] op_sel_hi:[0,1]
	v_pk_fma_f32 v[6:7], v[24:25], v[6:7], v[26:27] op_sel_hi:[0,1,1]
	v_pk_fma_f32 v[4:5], v[12:13], v[46:47], v[4:5] op_sel_hi:[0,1,1]
	v_pk_fma_f32 v[6:7], v[10:11], v[8:9], v[6:7] op_sel_hi:[0,1,1]
	v_pk_add_f32 v[4:5], v[16:17], v[4:5] op_sel_hi:[0,1]
	v_pk_add_f32 v[6:7], v[14:15], v[6:7] op_sel_hi:[0,1]
	v_pk_mul_f32 v[4:5], v[4:5], v[6:7]
	v_cvt_pk_bf16_f32 v2, v2, v3
	v_cvt_pk_bf16_f32 v3, v4, v5
	v_pk_mov_b32 v[4:5], v[46:47], v[28:29] op_sel:[1,0]
	v_pk_mov_b32 v[6:7], v[8:9], v[34:35] op_sel:[1,0]
	v_pk_mul_f32 v[4:5], v[20:21], v[4:5] op_sel_hi:[0,1]
	v_pk_mul_f32 v[6:7], v[18:19], v[6:7] op_sel_hi:[0,1]
	v_pk_fma_f32 v[4:5], v[22:23], v[46:47], v[4:5] op_sel_hi:[0,1,1]
	v_pk_fma_f32 v[6:7], v[24:25], v[8:9], v[6:7] op_sel_hi:[0,1,1]
	v_pk_fma_f32 v[4:5], v[12:13], v[28:29], v[4:5] op_sel_hi:[0,1,1]
	v_pk_fma_f32 v[6:7], v[10:11], v[34:35], v[6:7] op_sel_hi:[0,1,1]
	v_mov_b32_e32 v32, v29
	v_mov_b32_e32 v36, v35
	v_pk_add_f32 v[4:5], v[16:17], v[4:5] op_sel_hi:[0,1]
	v_pk_add_f32 v[6:7], v[14:15], v[6:7] op_sel_hi:[0,1]
	v_pk_mul_f32 v[4:5], v[4:5], v[6:7]
	v_pk_mul_f32 v[6:7], v[20:21], v[32:33] op_sel_hi:[0,1]
	v_pk_mul_f32 v[8:9], v[18:19], v[36:37] op_sel_hi:[0,1]
	v_pk_fma_f32 v[6:7], v[22:23], v[28:29], v[6:7] op_sel_hi:[0,1,1]
	v_mov_b32_e32 v22, v33
	v_pk_fma_f32 v[8:9], v[24:25], v[34:35], v[8:9] op_sel_hi:[0,1,1]
	v_mov_b32_e32 v24, v37
	v_pk_fma_f32 v[6:7], v[12:13], v[22:23], v[6:7] op_sel_hi:[0,1,1]
	v_pk_fma_f32 v[8:9], v[10:11], v[24:25], v[8:9] op_sel_hi:[0,1,1]
	v_pk_add_f32 v[6:7], v[16:17], v[6:7] op_sel_hi:[0,1]
	v_pk_add_f32 v[8:9], v[14:15], v[8:9] op_sel_hi:[0,1]
	v_pk_mul_f32 v[6:7], v[6:7], v[8:9]
	v_cvt_pk_bf16_f32 v4, v4, v5
	v_cvt_pk_bf16_f32 v5, v6, v7
	v_add_u32_e32 v6, 0x100, v62
	s_movk_i32 s0, 0x780
	v_ashrrev_i32_e32 v6, 1, v6
	v_mul_lo_u32 v7, v60, s0
	v_lshlrev_b32_e32 v65, 1, v62
	v_and_b32_e32 v6, -16, v6
	v_add3_u32 v6, v7, v65, v6
	v_add_u32_e32 v70, 0x100, v41
	ds_write_b128 v6, v[2:5] offset:1664
	v_ashrrev_i32_e32 v2, 31, v70
	v_lshrrev_b32_e32 v71, 27, v2
	v_lshlrev_b32_e32 v48, 3, v70
	v_add_u32_e32 v2, v70, v71
	v_ashrrev_i32_e32 v49, 31, v48
	v_ashrrev_i32_e32 v66, 5, v2
	v_lshlrev_b64 v[46:47], 1, v[48:49]
	v_lshlrev_b32_e32 v2, 8, v66
	v_lshl_add_u64 v[24:25], s[28:29], 0, v[46:47]
	v_lshl_add_u64 v[22:23], s[38:39], 0, v[46:47]
	v_sub_u32_e32 v67, v48, v2
	global_load_dwordx4 v[2:5], v[24:25], off
	global_load_dwordx4 v[6:9], v[22:23], off
	v_cmp_lt_i32_e32 vcc, 0, v67
	v_mov_b32_e32 v31, 0
	v_mov_b32_e32 v35, 0
	s_and_saveexec_b64 s[0:1], vcc
	s_cbranch_execz .LBB0_392
	global_load_ushort v35, v[24:25], off offset:-2
.LBB0_392:
	s_or_b64 exec, exec, s[0:1]
	s_movk_i32 s0, 0xf8
	v_cmp_gt_i32_e64 s[0:1], s0, v67
	s_and_saveexec_b64 s[40:41], s[0:1]
	s_cbranch_execz .LBB0_394
	global_load_ushort v31, v[24:25], off offset:16
.LBB0_394:
	s_or_b64 exec, exec, s[40:41]
	v_mov_b32_e32 v33, 0
	v_mov_b32_e32 v37, 0
	s_and_saveexec_b64 s[40:41], vcc
	s_cbranch_execz .LBB0_396
	global_load_ushort v37, v[22:23], off offset:-2
.LBB0_396:
	s_or_b64 exec, exec, s[40:41]
	s_and_saveexec_b64 s[40:41], s[0:1]
	s_cbranch_execz .LBB0_398
	global_load_ushort v33, v[22:23], off offset:16
.LBB0_398:
	s_or_b64 exec, exec, s[40:41]
	s_waitcnt vmcnt(0)
	v_lshlrev_b32_e32 v35, 16, v35
	v_lshlrev_b32_e32 v31, 16, v31
	v_lshlrev_b32_e32 v37, 16, v37
	v_lshlrev_b32_e32 v33, 16, v33
	v_lshlrev_b32_e32 v32, 16, v6
	v_lshlrev_b32_e32 v51, 16, v5
	v_and_b32_e32 v53, 0xffff0000, v5
	v_and_b32_e32 v54, 0xffff0000, v8
	v_lshlrev_b32_e32 v5, 16, v8
	v_and_b32_e32 v8, 0xffff0000, v2
	v_and_b32_e32 v6, 0xffff0000, v6
	v_mov_b32_e32 v34, v8
	v_mov_b32_e32 v36, v6
	v_lshlrev_b32_e32 v30, 16, v2
	v_lshlrev_b32_e32 v55, 16, v9
	v_and_b32_e32 v57, 0xffff0000, v9
	v_and_b32_e32 v58, 0xffff0000, v3
	v_lshlrev_b32_e32 v9, 16, v3
	v_pk_mul_f32 v[2:3], v[20:21], v[34:35]
	v_pk_mul_f32 v[34:35], v[18:19], v[36:37]
	v_mov_b32_e32 v13, v12
	v_mov_b32_e32 v11, v10
	v_and_b32_e32 v50, 0xffff0000, v4
	v_lshlrev_b32_e32 v59, 16, v4
	v_and_b32_e32 v4, 0xffff0000, v7
	v_lshlrev_b32_e32 v7, 16, v7
	v_pk_fma_f32 v[2:3], v[20:21], v[30:31], v[2:3] op_sel:[0,0,1] op_sel_hi:[1,0,0]
	v_pk_fma_f32 v[34:35], v[18:19], v[32:33], v[34:35] op_sel:[0,0,1] op_sel_hi:[1,0,0]
	v_mov_b32_e32 v17, v16
	v_mov_b32_e32 v15, v14
	v_pk_fma_f32 v[2:3], v[12:13], v[8:9], v[2:3]
	v_pk_fma_f32 v[34:35], v[10:11], v[6:7], v[34:35]
	v_pk_add_f32 v[2:3], v[16:17], v[2:3]
	v_pk_add_f32 v[34:35], v[14:15], v[34:35]
	v_mov_b32_e32 v28, v20
	v_mov_b32_e32 v29, v20
	v_pk_mul_f32 v[2:3], v[2:3], v[34:35]
	v_pk_mov_b32 v[34:35], v[8:9], v[58:59] op_sel:[1,0]
	v_mov_b32_e32 v24, v21
	v_mov_b32_e32 v25, v21
	v_pk_mul_f32 v[34:35], v[28:29], v[34:35]
	v_mov_b32_e32 v26, v18
	v_mov_b32_e32 v27, v18
	v_pk_fma_f32 v[8:9], v[24:25], v[8:9], v[34:35]
	v_pk_mov_b32 v[34:35], v[6:7], v[4:5] op_sel:[1,0]
	v_mov_b32_e32 v22, v19
	v_mov_b32_e32 v23, v19
	v_pk_mul_f32 v[34:35], v[26:27], v[34:35]
	v_pk_fma_f32 v[8:9], v[12:13], v[58:59], v[8:9]
	v_pk_fma_f32 v[6:7], v[22:23], v[6:7], v[34:35]
	v_pk_add_f32 v[8:9], v[16:17], v[8:9]
	v_pk_fma_f32 v[6:7], v[10:11], v[4:5], v[6:7]
	v_cvt_pk_bf16_f32 v2, v2, v3
	v_pk_add_f32 v[6:7], v[14:15], v[6:7]
	v_mov_b32_e32 v52, v51
	v_pk_mul_f32 v[6:7], v[8:9], v[6:7]
	v_pk_mov_b32 v[8:9], v[4:5], v[54:55] op_sel:[1,0]
	v_cvt_pk_bf16_f32 v3, v6, v7
	v_pk_mov_b32 v[6:7], v[58:59], v[50:51] op_sel:[1,0]
	v_pk_mul_f32 v[8:9], v[26:27], v[8:9]
	v_pk_mul_f32 v[6:7], v[28:29], v[6:7]
	v_pk_fma_f32 v[4:5], v[22:23], v[4:5], v[8:9]
	v_pk_fma_f32 v[6:7], v[24:25], v[58:59], v[6:7]
	v_pk_fma_f32 v[4:5], v[10:11], v[54:55], v[4:5]
	v_pk_fma_f32 v[6:7], v[12:13], v[50:51], v[6:7]
	v_mov_b32_e32 v56, v55
	v_pk_add_f32 v[6:7], v[16:17], v[6:7]
	v_pk_add_f32 v[4:5], v[14:15], v[4:5]
	v_pk_mul_f32 v[8:9], v[26:27], v[56:57]
	v_pk_mul_f32 v[4:5], v[6:7], v[4:5]
	v_pk_mul_f32 v[6:7], v[28:29], v[52:53]
	v_mov_b32_e32 v30, v53
	v_pk_fma_f32 v[6:7], v[24:25], v[50:51], v[6:7]
	v_pk_fma_f32 v[8:9], v[22:23], v[54:55], v[8:9]
	v_mov_b32_e32 v32, v57
	v_pk_fma_f32 v[6:7], v[12:13], v[30:31], v[6:7]
	v_pk_fma_f32 v[8:9], v[10:11], v[32:33], v[8:9]
	v_pk_add_f32 v[6:7], v[16:17], v[6:7]
	v_pk_add_f32 v[8:9], v[14:15], v[8:9]
	v_cvt_pk_bf16_f32 v4, v4, v5
	v_pk_mul_f32 v[6:7], v[6:7], v[8:9]
	s_movk_i32 s0, 0x780
	v_cvt_pk_bf16_f32 v5, v6, v7
	v_add_u32_e32 v6, 0x100, v67
	v_ashrrev_i32_e32 v6, 1, v6
	v_mul_lo_u32 v7, v66, s0
	v_lshlrev_b32_e32 v72, 1, v67
	v_and_b32_e32 v6, -16, v6
	v_add3_u32 v6, v7, v72, v6
	ds_write_b128 v6, v[2:5] offset:1664
	v_ashrrev_i32_e32 v2, 31, v64
	v_lshrrev_b32_e32 v76, 27, v2
	v_lshlrev_b32_e32 v52, 3, v64
	v_add_u32_e32 v2, v64, v76
	v_ashrrev_i32_e32 v53, 31, v52
	v_ashrrev_i32_e32 v68, 5, v2
	v_lshlrev_b64 v[50:51], 1, v[52:53]
	v_lshlrev_b32_e32 v2, 8, v68
	v_lshl_add_u64 v[32:33], s[28:29], 0, v[50:51]
	v_lshl_add_u64 v[30:31], s[38:39], 0, v[50:51]
	v_sub_u32_e32 v69, v52, v2
	global_load_dwordx4 v[2:5], v[32:33], off
	global_load_dwordx4 v[6:9], v[30:31], off
	v_cmp_lt_i32_e32 vcc, 0, v69
	v_mov_b32_e32 v35, 0
	v_mov_b32_e32 v37, 0
	s_and_saveexec_b64 s[0:1], vcc
	s_cbranch_execz .LBB0_400
	global_load_ushort v37, v[32:33], off offset:-2
.LBB0_400:
	s_or_b64 exec, exec, s[0:1]
	s_movk_i32 s0, 0xf8
	v_cmp_gt_i32_e64 s[0:1], s0, v69
	s_and_saveexec_b64 s[40:41], s[0:1]
	s_cbranch_execz .LBB0_402
	global_load_ushort v35, v[32:33], off offset:16
.LBB0_402:
	s_or_b64 exec, exec, s[40:41]
	v_mov_b32_e32 v33, 0
	v_mov_b32_e32 v55, 0
	s_and_saveexec_b64 s[40:41], vcc
	s_cbranch_execz .LBB0_404
	global_load_ushort v55, v[30:31], off offset:-2
.LBB0_404:
	s_or_b64 exec, exec, s[40:41]
	s_and_saveexec_b64 s[40:41], s[0:1]
	s_cbranch_execz .LBB0_406
	global_load_ushort v33, v[30:31], off offset:16
.LBB0_406:
	s_or_b64 exec, exec, s[40:41]
	s_waitcnt vmcnt(0)
	v_lshlrev_b32_e32 v37, 16, v37
	v_lshlrev_b32_e32 v35, 16, v35
	v_lshlrev_b32_e32 v55, 16, v55
	v_lshlrev_b32_e32 v33, 16, v33
	v_lshlrev_b32_e32 v57, 16, v5
	v_and_b32_e32 v59, 0xffff0000, v5
	s_waitcnt vmcnt(0)
	v_and_b32_e32 v74, 0xffff0000, v8
	v_lshlrev_b32_e32 v5, 16, v8
	v_and_b32_e32 v8, 0xffff0000, v2
	v_lshlrev_b32_e32 v32, 16, v6
	v_and_b32_e32 v6, 0xffff0000, v6
	v_mov_b32_e32 v36, v8
	v_lshlrev_b32_e32 v30, 16, v2
	v_lshlrev_b32_e32 v75, 16, v9
	v_and_b32_e32 v79, 0xffff0000, v9
	v_and_b32_e32 v80, 0xffff0000, v3
	v_lshlrev_b32_e32 v9, 16, v3
	v_pk_mul_f32 v[2:3], v[20:21], v[36:37]
	v_mov_b32_e32 v54, v6
	v_pk_fma_f32 v[2:3], v[20:21], v[30:31], v[2:3] op_sel:[0,0,1] op_sel_hi:[1,0,0]
	v_pk_mul_f32 v[30:31], v[18:19], v[54:55]
	v_and_b32_e32 v56, 0xffff0000, v4
	v_lshlrev_b32_e32 v81, 16, v4
	v_and_b32_e32 v4, 0xffff0000, v7
	v_lshlrev_b32_e32 v7, 16, v7
	v_pk_fma_f32 v[30:31], v[18:19], v[32:33], v[30:31] op_sel:[0,0,1] op_sel_hi:[1,0,0]
	v_pk_fma_f32 v[2:3], v[12:13], v[8:9], v[2:3]
	v_pk_fma_f32 v[30:31], v[10:11], v[6:7], v[30:31]
	v_pk_add_f32 v[2:3], v[16:17], v[2:3]
	v_pk_add_f32 v[30:31], v[14:15], v[30:31]
	v_mov_b32_e32 v58, v57
	v_pk_mul_f32 v[2:3], v[2:3], v[30:31]
	v_pk_mov_b32 v[30:31], v[8:9], v[80:81] op_sel:[1,0]
	v_cvt_pk_bf16_f32 v2, v2, v3
	v_pk_mul_f32 v[30:31], v[28:29], v[30:31]
	v_mov_b32_e32 v78, v75
	v_pk_fma_f32 v[8:9], v[24:25], v[8:9], v[30:31]
	v_pk_mov_b32 v[30:31], v[6:7], v[4:5] op_sel:[1,0]
	v_pk_fma_f32 v[8:9], v[12:13], v[80:81], v[8:9]
	v_pk_mul_f32 v[30:31], v[26:27], v[30:31]
	v_pk_add_f32 v[8:9], v[16:17], v[8:9]
	v_pk_fma_f32 v[6:7], v[22:23], v[6:7], v[30:31]
	v_mov_b32_e32 v34, v59
	v_pk_fma_f32 v[6:7], v[10:11], v[4:5], v[6:7]
	v_mov_b32_e32 v32, v79
	v_pk_add_f32 v[6:7], v[14:15], v[6:7]
	s_movk_i32 s0, 0x780
	v_pk_mul_f32 v[6:7], v[8:9], v[6:7]
	v_pk_mov_b32 v[8:9], v[4:5], v[74:75] op_sel:[1,0]
	v_cvt_pk_bf16_f32 v3, v6, v7
	v_pk_mov_b32 v[6:7], v[80:81], v[56:57] op_sel:[1,0]
	v_pk_mul_f32 v[8:9], v[26:27], v[8:9]
	v_pk_mul_f32 v[6:7], v[28:29], v[6:7]
	v_pk_fma_f32 v[4:5], v[22:23], v[4:5], v[8:9]
	v_pk_fma_f32 v[6:7], v[24:25], v[80:81], v[6:7]
	v_pk_fma_f32 v[4:5], v[10:11], v[74:75], v[4:5]
	v_pk_fma_f32 v[6:7], v[12:13], v[56:57], v[6:7]
	v_pk_add_f32 v[4:5], v[14:15], v[4:5]
	v_pk_add_f32 v[6:7], v[16:17], v[6:7]
	v_pk_mul_f32 v[8:9], v[26:27], v[78:79]
	v_pk_mul_f32 v[4:5], v[6:7], v[4:5]
	v_pk_mul_f32 v[6:7], v[28:29], v[58:59]
	v_pk_fma_f32 v[8:9], v[22:23], v[74:75], v[8:9]
	v_pk_fma_f32 v[6:7], v[24:25], v[56:57], v[6:7]
	v_pk_fma_f32 v[8:9], v[10:11], v[32:33], v[8:9]
	v_pk_fma_f32 v[6:7], v[12:13], v[34:35], v[6:7]
	v_pk_add_f32 v[8:9], v[14:15], v[8:9]
	v_pk_add_f32 v[6:7], v[16:17], v[6:7]
	v_cvt_pk_bf16_f32 v4, v4, v5
	v_pk_mul_f32 v[6:7], v[6:7], v[8:9]
	v_lshlrev_b32_e32 v73, 1, v69
	v_cvt_pk_bf16_f32 v5, v6, v7
	v_add_u32_e32 v6, 0x100, v69
	v_ashrrev_i32_e32 v6, 1, v6
	v_mul_lo_u32 v7, v68, s0
	v_and_b32_e32 v6, -16, v6
	v_add3_u32 v6, v7, v73, v6
	v_add_u32_e32 v78, 0x300, v41
	ds_write_b128 v6, v[2:5] offset:1664
	v_ashrrev_i32_e32 v2, 31, v78
	v_lshrrev_b32_e32 v79, 27, v2
	v_lshlrev_b32_e32 v56, 3, v78
	v_add_u32_e32 v2, v78, v79
	v_ashrrev_i32_e32 v57, 31, v56
	v_ashrrev_i32_e32 v74, 5, v2
	v_lshlrev_b64 v[54:55], 1, v[56:57]
	v_lshlrev_b32_e32 v2, 8, v74
	v_lshl_add_u64 v[32:33], s[28:29], 0, v[54:55]
	v_lshl_add_u64 v[30:31], s[38:39], 0, v[54:55]
	v_sub_u32_e32 v75, v56, v2
	global_load_dwordx4 v[2:5], v[32:33], off
	global_load_dwordx4 v[6:9], v[30:31], off
	v_cmp_lt_i32_e32 vcc, 0, v75
	v_mov_b32_e32 v35, 0
	v_mov_b32_e32 v37, 0
	s_and_saveexec_b64 s[0:1], vcc
	s_cbranch_execz .LBB0_408
	global_load_ushort v37, v[32:33], off offset:-2
.LBB0_408:
	s_or_b64 exec, exec, s[0:1]
	s_movk_i32 s0, 0xf8
	v_cmp_gt_i32_e64 s[0:1], s0, v75
	s_and_saveexec_b64 s[28:29], s[0:1]
	s_cbranch_execz .LBB0_410
	global_load_ushort v35, v[32:33], off offset:16
.LBB0_410:
	s_or_b64 exec, exec, s[28:29]
	v_mov_b32_e32 v33, 0
	v_mov_b32_e32 v59, 0
	s_and_saveexec_b64 s[28:29], vcc
	s_cbranch_execz .LBB0_412
	global_load_ushort v59, v[30:31], off offset:-2
.LBB0_412:
	s_or_b64 exec, exec, s[28:29]
	s_and_saveexec_b64 s[28:29], s[0:1]
	s_cbranch_execz .LBB0_414
	global_load_ushort v33, v[30:31], off offset:16
.LBB0_414:
	s_or_b64 exec, exec, s[28:29]
	s_waitcnt vmcnt(0)
	v_lshlrev_b32_e32 v37, 16, v37
	v_lshlrev_b32_e32 v35, 16, v35
	v_lshlrev_b32_e32 v59, 16, v59
	v_lshlrev_b32_e32 v33, 16, v33
	v_lshlrev_b32_e32 v81, 16, v5
	v_and_b32_e32 v83, 0xffff0000, v5
	s_waitcnt vmcnt(0)
	v_and_b32_e32 v84, 0xffff0000, v8
	v_lshlrev_b32_e32 v5, 16, v8
	v_and_b32_e32 v8, 0xffff0000, v2
	v_lshlrev_b32_e32 v32, 16, v6
	v_and_b32_e32 v6, 0xffff0000, v6
	v_mov_b32_e32 v36, v8
	v_and_b32_e32 v31, 31, v41
	v_lshlrev_b32_e32 v30, 16, v2
	v_lshlrev_b32_e32 v85, 16, v9
	v_and_b32_e32 v87, 0xffff0000, v9
	v_and_b32_e32 v88, 0xffff0000, v3
	v_lshlrev_b32_e32 v9, 16, v3
	v_pk_mul_f32 v[2:3], v[20:21], v[36:37]
	v_mov_b32_e32 v58, v6
	v_pk_fma_f32 v[2:3], v[20:21], v[30:31], v[2:3] op_sel:[0,0,1] op_sel_hi:[1,0,0]
	v_pk_mul_f32 v[20:21], v[18:19], v[58:59]
	v_and_b32_e32 v80, 0xffff0000, v4
	v_lshlrev_b32_e32 v89, 16, v4
	v_and_b32_e32 v4, 0xffff0000, v7
	v_lshlrev_b32_e32 v7, 16, v7
	v_pk_fma_f32 v[18:19], v[18:19], v[32:33], v[20:21] op_sel:[0,0,1] op_sel_hi:[1,0,0]
	v_pk_fma_f32 v[2:3], v[12:13], v[8:9], v[2:3]
	v_pk_fma_f32 v[18:19], v[10:11], v[6:7], v[18:19]
	v_pk_add_f32 v[2:3], v[16:17], v[2:3]
	v_pk_add_f32 v[18:19], v[14:15], v[18:19]
	v_mov_b32_e32 v82, v81
	v_pk_mul_f32 v[2:3], v[2:3], v[18:19]
	v_pk_mov_b32 v[18:19], v[8:9], v[88:89] op_sel:[1,0]
	v_cvt_pk_bf16_f32 v2, v2, v3
	v_pk_mul_f32 v[18:19], v[28:29], v[18:19]
	v_mov_b32_e32 v86, v85
	v_pk_fma_f32 v[8:9], v[24:25], v[8:9], v[18:19]
	v_pk_mov_b32 v[18:19], v[6:7], v[4:5] op_sel:[1,0]
	v_pk_fma_f32 v[8:9], v[12:13], v[88:89], v[8:9]
	v_pk_mul_f32 v[18:19], v[26:27], v[18:19]
	v_pk_add_f32 v[8:9], v[16:17], v[8:9]
	v_pk_fma_f32 v[6:7], v[22:23], v[6:7], v[18:19]
	v_mov_b32_e32 v34, v83
	v_pk_fma_f32 v[6:7], v[10:11], v[4:5], v[6:7]
	v_mov_b32_e32 v32, v87
	v_pk_add_f32 v[6:7], v[14:15], v[6:7]
	s_movk_i32 s0, 0x780
	v_pk_mul_f32 v[6:7], v[8:9], v[6:7]
	v_pk_mov_b32 v[8:9], v[4:5], v[84:85] op_sel:[1,0]
	v_cvt_pk_bf16_f32 v3, v6, v7
	v_pk_mov_b32 v[6:7], v[88:89], v[80:81] op_sel:[1,0]
	v_pk_mul_f32 v[8:9], v[26:27], v[8:9]
	v_pk_mul_f32 v[6:7], v[28:29], v[6:7]
	v_pk_fma_f32 v[4:5], v[22:23], v[4:5], v[8:9]
	v_pk_fma_f32 v[6:7], v[24:25], v[88:89], v[6:7]
	v_pk_fma_f32 v[4:5], v[10:11], v[84:85], v[4:5]
	v_pk_fma_f32 v[6:7], v[12:13], v[80:81], v[6:7]
	v_pk_add_f32 v[4:5], v[14:15], v[4:5]
	v_pk_add_f32 v[6:7], v[16:17], v[6:7]
	v_pk_mul_f32 v[8:9], v[26:27], v[86:87]
	v_pk_mul_f32 v[4:5], v[6:7], v[4:5]
	v_pk_mul_f32 v[6:7], v[28:29], v[82:83]
	v_pk_fma_f32 v[8:9], v[22:23], v[84:85], v[8:9]
	v_pk_fma_f32 v[6:7], v[24:25], v[80:81], v[6:7]
	v_pk_fma_f32 v[8:9], v[10:11], v[32:33], v[8:9]
	v_pk_fma_f32 v[6:7], v[12:13], v[34:35], v[6:7]
	v_pk_add_f32 v[8:9], v[14:15], v[8:9]
	v_pk_add_f32 v[6:7], v[16:17], v[6:7]
	v_cvt_pk_bf16_f32 v4, v4, v5
	v_pk_mul_f32 v[6:7], v[6:7], v[8:9]
	v_lshlrev_b32_e32 v77, 1, v75
	v_cvt_pk_bf16_f32 v5, v6, v7
	v_add_u32_e32 v6, 0x100, v75
	v_ashrrev_i32_e32 v6, 1, v6
	v_mul_lo_u32 v7, v74, s0
	v_and_b32_e32 v6, -16, v6
	v_add3_u32 v6, v7, v77, v6
	ds_write_b128 v6, v[2:5] offset:1664
	v_lshrrev_b32_e32 v2, 2, v41
	v_and_b32_e32 v49, 8, v2
	v_or_b32_e32 v3, 7, v49
	v_lshlrev_b32_e32 v5, 1, v31
	v_bitop3_b32 v2, v2, 8, v2 bitop3:0xc
	v_sub_u32_e32 v3, v31, v3
	v_lshl_add_u32 v2, v2, 1, v5
	v_lshlrev_b32_e32 v3, 1, v3
	s_waitcnt lgkmcnt(0)
	s_barrier
	ds_read_b32 v6, v2 offset:14
	ds_read_b96 v[2:4], v3 offset:32
	s_movk_i32 s1, 0xffef
	s_waitcnt lgkmcnt(1)
	v_alignbit_b32 v34, v6, v6, 16
	s_waitcnt lgkmcnt(0)
	v_alignbit_b32 v36, v3, v3, 16
	v_lshlrev_b32_e32 v3, 5, v41
	v_and_b32_e32 v57, 0xe0, v3
	v_add_u32_e32 v3, 0x1f0, v57
	v_alignbit_b32 v35, v4, v4, 16
	v_or_b32_e32 v4, v3, v49
	v_lshrrev_b32_e32 v3, 2, v3
	v_and_b32_e32 v3, 0xf8, v3
	v_alignbit_b32 v37, v2, v2, 16
	v_bfe_u32 v2, v41, 3, 2
	v_add_u32_e32 v80, v4, v3
	v_lshrrev_b32_e32 v3, 1, v41
	v_lshl_or_b32 v53, v61, 3, v2
	v_and_b32_e32 v3, 16, v3
	v_mul_lo_u32 v58, v53, s0
	v_sub_u32_e32 v4, v5, v3
	s_movk_i32 s0, 0x3c00
	v_and_b32_e32 v5, 7, v41
	v_add_u32_e32 v59, 50, v4
	v_mul_lo_u32 v4, v61, s0
	v_mul_u32_u24_e32 v2, 0x780, v2
	v_lshlrev_b32_e32 v5, 6, v5
	v_add3_u32 v2, v4, v2, v5
	v_or_b32_e32 v61, v2, v3
	v_mov_b32_e32 v2, 0
	v_add_u32_e32 v63, 0x1d0, v57
	s_mov_b32 s0, -15
	v_mov_b32_e32 v3, v2
	v_mov_b32_e32 v4, v2
	v_mov_b32_e32 v5, v2
	v_mov_b32_e32 v6, v2
	v_mov_b32_e32 v7, v2
	v_mov_b32_e32 v8, v2
	v_mov_b32_e32 v9, v2
	v_mov_b32_e32 v10, v2
	v_mov_b32_e32 v11, v2
	v_mov_b32_e32 v12, v2
	v_mov_b32_e32 v13, v2
	v_mov_b32_e32 v14, v2
	v_mov_b32_e32 v15, v2
	v_mov_b32_e32 v16, v2
	v_mov_b32_e32 v17, v2
	v_mov_b32_e32 v18, v2
	v_mov_b32_e32 v19, v2
	v_mov_b32_e32 v20, v2
	v_mov_b32_e32 v21, v2
	v_mov_b32_e32 v22, v2
	v_mov_b32_e32 v23, v2
	v_mov_b32_e32 v24, v2
	v_mov_b32_e32 v25, v2
	v_mov_b32_e32 v26, v2
	v_mov_b32_e32 v27, v2
	v_mov_b32_e32 v28, v2
	v_mov_b32_e32 v29, v2
	v_mov_b32_e32 v30, v2
	v_mov_b32_e32 v31, v2
	v_mov_b32_e32 v32, v2
	v_mov_b32_e32 v33, v2
.LBB0_415:
	v_lshl_add_u32 v92, v80, 1, v58
	ds_read_b128 v[80:83], v59
	ds_read_b128 v[84:87], v59 offset:32
	ds_read_b128 v[88:91], v92 offset:1152
	v_add_u32_e32 v93, 16, v63
	s_add_i32 s0, s0, 2
	s_waitcnt lgkmcnt(2)
	v_alignbit_b32 v97, v82, v82, 16
	s_waitcnt lgkmcnt(0)
	v_mfma_f32_32x32x16_bf16 v[2:17], v[34:37], v[88:91], v[2:17]
	ds_read_b128 v[88:91], v92 offset:8832
	v_ashrrev_i32_e32 v92, 5, v93
	v_lshl_add_u32 v101, v92, 4, v61
	ds_read_b128 v[92:95], v101 offset:2112
	v_alignbit_b32 v96, v83, v83, 16
	v_alignbit_b32 v98, v81, v81, 16
	v_alignbit_b32 v99, v80, v80, 16
	s_waitcnt lgkmcnt(1)
	v_mfma_f32_32x32x16_bf16 v[18:33], v[34:37], v[88:91], v[18:33]
	ds_read_b128 v[34:37], v101 offset:9792
	s_lshl_b32 s4, s0, 4
	v_lshrrev_b32_e32 v100, 2, v63
	v_subrev_u32_e32 v81, s4, v57
	s_add_i32 s1, s1, 2
	v_and_b32_e32 v80, 0x3ffffff8, v100
	v_add_u32_e32 v59, 64, v59
	s_waitcnt lgkmcnt(1)
	v_mfma_f32_32x32x16_bf16 v[2:17], v[96:99], v[92:95], v[2:17]
	v_subrev_u32_e32 v63, 32, v63
	v_subrev_u32_e32 v61, 64, v61
	s_cmp_gt_i32 s1, 12
	s_waitcnt lgkmcnt(0)
	v_mfma_f32_32x32x16_bf16 v[18:33], v[96:99], v[34:37], v[18:33]
	v_add_u32_e32 v34, v81, v49
	v_add3_u32 v80, v34, v80, s17
	v_alignbit_b32 v34, v87, v87, 16
	v_alignbit_b32 v35, v86, v86, 16
	v_alignbit_b32 v36, v85, v85, 16
	v_alignbit_b32 v37, v84, v84, 16
	s_cbranch_scc0 .LBB0_415
	s_movk_i32 s0, 0x220
	v_lshl_add_u32 v34, v57, 1, v49
	v_mul_lo_u32 v35, v53, s0
	v_lshrrev_b32_e32 v36, 3, v57
	v_add3_u32 v34, v34, v35, v36
	v_add_u32_e32 v35, 0x480, v34
	v_cvt_pk_bf16_f32 v4, v4, v5
	v_cvt_pk_bf16_f32 v2, v2, v3
	s_barrier
	ds_write2_b32 v35, v2, v4 offset1:1
	v_cvt_pk_bf16_f32 v3, v8, v9
	v_cvt_pk_bf16_f32 v2, v6, v7
	v_cvt_pk_bf16_f32 v5, v12, v13
	v_cvt_pk_bf16_f32 v4, v10, v11
	s_mul_i32 s0, s50, 0xc000
	v_readlane_b32 s4, v253, 40
	ds_write2_b64 v34, v[2:3], v[4:5] offset0:146 offset1:148
	v_cvt_pk_bf16_f32 v3, v16, v17
	v_cvt_pk_bf16_f32 v2, v14, v15
	s_mul_hi_u32 s1, s50, 0xc000
	s_add_u32 s28, s4, s0
	v_readlane_b32 s4, v253, 41
	ds_write_b64 v34, v[2:3] offset:1200
	v_add_u32_e32 v2, 0xd00, v34
	v_cvt_pk_bf16_f32 v3, v20, v21
	v_cvt_pk_bf16_f32 v4, v18, v19
	s_addc_u32 s29, s4, s1
	v_readlane_b32 s4, v253, 50
	ds_write2_b32 v2, v4, v3 offset1:1
	v_cvt_pk_bf16_f32 v3, v24, v25
	v_cvt_pk_bf16_f32 v2, v22, v23
	v_cvt_pk_bf16_f32 v5, v28, v29
	v_cvt_pk_bf16_f32 v4, v26, v27
	v_add_u32_e32 v6, 0x800, v34
	s_add_u32 s0, s4, s0
	v_readlane_b32 s4, v253, 51
	ds_write2_b64 v6, v[2:3], v[4:5] offset0:162 offset1:164
	v_cvt_pk_bf16_f32 v3, v32, v33
	v_cvt_pk_bf16_f32 v2, v30, v31
	s_addc_u32 s1, s4, s1
	v_lshl_add_u64 v[58:59], s[28:29], 0, v[44:45]
	ds_write_b64 v34, v[2:3] offset:3376
	s_waitcnt lgkmcnt(0)
	s_barrier
	v_lshl_add_u64 v[2:3], s[0:1], 0, v[44:45]
	global_load_dwordx4 v[30:33], v[58:59], off
	global_load_dwordx4 v[26:29], v[2:3], off
	v_add_lshl_u32 v2, v41, v43, 3
	v_and_b32_e32 v2, 0xffffff00, v2
	v_sub_u32_e32 v2, v42, v2
	v_cmp_lt_i32_e32 vcc, 0, v2
	v_mov_b32_e32 v61, 0
	v_mov_b32_e32 v63, 0
	s_and_saveexec_b64 s[38:39], vcc
	s_cbranch_execz .LBB0_418
	global_load_ushort v63, v[58:59], off offset:-2
.LBB0_418:
	s_or_b64 exec, exec, s[38:39]
	s_movk_i32 s4, 0xf8
	v_cmp_gt_i32_e32 vcc, s4, v2
	s_and_saveexec_b64 s[38:39], vcc
	s_movk_i32 s50, 0x3000
	s_cbranch_execz .LBB0_420
	global_load_ushort v61, v[58:59], off offset:16
.LBB0_420:
	s_or_b64 exec, exec, s[38:39]
	v_add_lshl_u32 v2, v70, v71, 3
	v_and_b32_e32 v2, 0xffffff00, v2
	v_sub_u32_e32 v2, v48, v2
	v_lshl_add_u64 v[48:49], s[28:29], 0, v[46:47]
	v_lshl_add_u64 v[4:5], s[0:1], 0, v[46:47]
	global_load_dwordx4 v[22:25], v[48:49], off
	global_load_dwordx4 v[14:17], v[4:5], off
	v_cmp_lt_i32_e32 vcc, 0, v2
	v_mov_b32_e32 v53, 0
	v_mov_b32_e32 v57, 0
	s_and_saveexec_b64 s[38:39], vcc
	s_cbranch_execz .LBB0_422
	global_load_ushort v57, v[48:49], off offset:-2
.LBB0_422:
	s_or_b64 exec, exec, s[38:39]
	v_cmp_gt_i32_e32 vcc, s4, v2
	s_and_saveexec_b64 s[38:39], vcc
	s_cbranch_execz .LBB0_424
	global_load_ushort v53, v[48:49], off offset:16
.LBB0_424:
	s_or_b64 exec, exec, s[38:39]
	v_lshl_add_u64 v[44:45], s[28:29], 0, v[50:51]
	v_lshl_add_u64 v[4:5], s[0:1], 0, v[50:51]
	global_load_dwordx4 v[18:21], v[44:45], off
	global_load_dwordx4 v[10:13], v[4:5], off
	v_add_lshl_u32 v2, v64, v76, 3
	v_and_b32_e32 v2, 0xffffff00, v2
	v_sub_u32_e32 v2, v52, v2
	v_cmp_lt_i32_e32 vcc, 0, v2
	v_mov_b32_e32 v47, 0
	v_mov_b32_e32 v51, 0
	s_and_saveexec_b64 s[38:39], vcc
	s_cbranch_execz .LBB0_426
	global_load_ushort v51, v[44:45], off offset:-2
.LBB0_426:
	s_or_b64 exec, exec, s[38:39]
	v_cmp_gt_i32_e32 vcc, s4, v2
	s_and_saveexec_b64 s[38:39], vcc
	s_cbranch_execz .LBB0_428
	global_load_ushort v47, v[44:45], off offset:16
.LBB0_428:
	s_or_b64 exec, exec, s[38:39]
	v_add_lshl_u32 v2, v78, v79, 3
	v_and_b32_e32 v2, 0xffffff00, v2
	v_sub_u32_e32 v36, v56, v2
	v_lshl_add_u64 v[34:35], s[28:29], 0, v[54:55]
	v_lshl_add_u64 v[2:3], s[0:1], 0, v[54:55]
	global_load_dwordx4 v[6:9], v[34:35], off
	v_cmp_lt_i32_e32 vcc, 0, v36
	global_load_dwordx4 v[2:5], v[2:3], off
	v_mov_b32_e32 v37, 0
	v_mov_b32_e32 v43, 0
	s_and_saveexec_b64 s[0:1], vcc
	s_cbranch_execz .LBB0_430
	global_load_ushort v43, v[34:35], off offset:-2
.LBB0_430:
	s_or_b64 exec, exec, s[0:1]
	s_movk_i32 s0, 0xf8
	v_cmp_gt_i32_e32 vcc, s0, v36
	s_and_saveexec_b64 s[0:1], vcc
	s_cbranch_execz .LBB0_432
	global_load_ushort v37, v[34:35], off offset:16
.LBB0_432:
	s_or_b64 exec, exec, s[0:1]
	v_ashrrev_i32_e32 v42, 4, v62
	s_movk_i32 s0, 0x220
	v_lshlrev_b32_e32 v42, 1, v42
	v_mul_lo_u32 v41, v60, s0
	v_and_b32_e32 v42, -4, v42
	v_add3_u32 v41, v41, v65, v42
	v_add_u32_e32 v42, 0x480, v41
	s_barrier
	s_waitcnt vmcnt(0)
	v_lshlrev_b32_e32 v63, 16, v63
	v_lshlrev_b32_e32 v61, 16, v61
	v_lshlrev_b32_e32 v57, 16, v57
	v_lshlrev_b32_e32 v53, 16, v53
	v_lshlrev_b32_e32 v51, 16, v51
	v_lshlrev_b32_e32 v47, 16, v47
	v_lshlrev_b32_e32 v43, 16, v43
	v_lshlrev_b32_e32 v37, 16, v37
	v_lshlrev_b32_e32 v36, 16, v30
	v_and_b32_e32 v54, 0xffff0000, v32
	v_lshlrev_b32_e32 v55, 16, v33
	v_and_b32_e32 v65, 0xffff0000, v33
	v_and_b32_e32 v70, 0xffff0000, v31
	v_lshlrev_b32_e32 v71, 16, v32
	v_lshlrev_b32_e32 v33, 16, v31
	v_and_b32_e32 v32, 0xffff0000, v30
	ds_read2_b32 v[30:31], v42 offset1:1
	v_mov_b32_e32 v62, v32
	v_pk_mul_f32 v[62:63], v[38:39], v[62:63]
	v_add_u32_e32 v41, 0x488, v41
	v_pk_fma_f32 v[62:63], v[38:39], v[36:37], v[62:63] op_sel:[0,0,1] op_sel_hi:[1,0,0]
	s_waitcnt lgkmcnt(0)
	v_and_b32_e32 v79, 0xffff0000, v30
	v_pk_fma_f32 v[62:63], v[0:1], v[32:33], v[62:63] op_sel_hi:[0,1,1]
	v_lshlrev_b32_e32 v78, 16, v30
	v_pk_add_f32 v[62:63], v[40:41], v[62:63] op_sel_hi:[0,1]
	s_waitcnt vmcnt(6)
	v_and_b32_e32 v81, 0xffff0000, v26
	v_lshlrev_b32_e32 v80, 16, v26
	v_pk_mul_f32 v[62:63], v[62:63], v[78:79]
	v_mov_b32_e32 v26, v39
	v_pk_mul_f32 v[62:63], v[62:63], v[80:81]
	v_pk_mov_b32 v[80:81], v[32:33], v[70:71] op_sel:[1,0]
	v_cvt_pk_bf16_f32 v30, v62, v63
	v_pk_mul_f32 v[80:81], v[38:39], v[80:81] op_sel_hi:[0,1]
	v_pk_fma_f32 v[32:33], v[26:27], v[32:33], v[80:81] op_sel_hi:[0,1,1]
	v_pk_fma_f32 v[32:33], v[0:1], v[70:71], v[32:33] op_sel_hi:[0,1,1]
	v_and_b32_e32 v63, 0xffff0000, v31
	v_lshlrev_b32_e32 v62, 16, v31
	v_pk_add_f32 v[32:33], v[40:41], v[32:33] op_sel_hi:[0,1]
	v_and_b32_e32 v79, 0xffff0000, v27
	v_lshlrev_b32_e32 v78, 16, v27
	v_pk_mul_f32 v[32:33], v[32:33], v[62:63]
	v_pk_mov_b32 v[80:81], v[70:71], v[54:55] op_sel:[1,0]
	v_pk_mul_f32 v[32:33], v[32:33], v[78:79]
	v_pk_mul_f32 v[80:81], v[38:39], v[80:81] op_sel_hi:[0,1]
	v_cvt_pk_bf16_f32 v31, v32, v33
	ds_read2_b32 v[32:33], v41 offset1:1
	v_pk_fma_f32 v[70:71], v[26:27], v[70:71], v[80:81] op_sel_hi:[0,1,1]
	v_pk_fma_f32 v[70:71], v[0:1], v[54:55], v[70:71] op_sel_hi:[0,1,1]
	v_pk_add_f32 v[70:71], v[40:41], v[70:71] op_sel_hi:[0,1]
	v_and_b32_e32 v79, 0xffff0000, v28
	s_waitcnt lgkmcnt(0)
	v_and_b32_e32 v63, 0xffff0000, v32
	v_lshlrev_b32_e32 v62, 16, v32
	v_lshlrev_b32_e32 v78, 16, v28
	v_pk_mul_f32 v[62:63], v[70:71], v[62:63]
	v_mov_b32_e32 v64, v55
	v_pk_mul_f32 v[62:63], v[62:63], v[78:79]
	v_mov_b32_e32 v60, v65
	v_cvt_pk_bf16_f32 v32, v62, v63
	v_pk_mul_f32 v[62:63], v[38:39], v[64:65] op_sel_hi:[0,1]
	v_pk_fma_f32 v[54:55], v[26:27], v[54:55], v[62:63] op_sel_hi:[0,1,1]
	v_pk_fma_f32 v[54:55], v[0:1], v[60:61], v[54:55] op_sel_hi:[0,1,1]
	v_pk_add_f32 v[54:55], v[40:41], v[54:55] op_sel_hi:[0,1]
	v_and_b32_e32 v61, 0xffff0000, v33
	v_lshlrev_b32_e32 v60, 16, v33
	v_pk_mul_f32 v[54:55], v[54:55], v[60:61]
	v_and_b32_e32 v61, 0xffff0000, v29
	v_lshlrev_b32_e32 v60, 16, v29
	v_pk_mul_f32 v[28:29], v[54:55], v[60:61]
	v_mul_lo_u32 v27, v66, s0
	v_cvt_pk_bf16_f32 v33, v28, v29
	v_ashrrev_i32_e32 v28, 4, v67
	v_lshlrev_b32_e32 v28, 1, v28
	v_and_b32_e32 v28, -4, v28
	v_add3_u32 v27, v27, v72, v28
	v_add_u32_e32 v41, 0x480, v27
	global_store_dwordx4 v[58:59], v[30:33], off
	s_waitcnt vmcnt(6)
	v_lshlrev_b32_e32 v36, 16, v22
	v_and_b32_e32 v28, 0xffff0000, v24
	v_lshlrev_b32_e32 v29, 16, v25
	v_and_b32_e32 v31, 0xffff0000, v25
	v_lshlrev_b32_e32 v33, 16, v24
	v_and_b32_e32 v22, 0xffff0000, v22
	ds_read2_b32 v[24:25], v41 offset1:1
	v_mov_b32_e32 v56, v22
	v_pk_mul_f32 v[56:57], v[38:39], v[56:57]
	v_and_b32_e32 v32, 0xffff0000, v23
	v_lshlrev_b32_e32 v23, 16, v23
	v_pk_fma_f32 v[56:57], v[38:39], v[36:37], v[56:57] op_sel:[0,0,1] op_sel_hi:[1,0,0]
	s_waitcnt lgkmcnt(0)
	v_and_b32_e32 v55, 0xffff0000, v24
	v_pk_fma_f32 v[56:57], v[0:1], v[22:23], v[56:57] op_sel_hi:[0,1,1]
	v_lshlrev_b32_e32 v54, 16, v24
	v_pk_add_f32 v[56:57], v[40:41], v[56:57] op_sel_hi:[0,1]
	v_pk_mul_f32 v[54:55], v[56:57], v[54:55]
	v_pk_mov_b32 v[56:57], v[22:23], v[32:33] op_sel:[1,0]
	v_add_u32_e32 v27, 0x488, v27
	v_pk_mul_f32 v[56:57], v[38:39], v[56:57] op_sel_hi:[0,1]
	s_waitcnt vmcnt(5)
	v_and_b32_e32 v59, 0xffff0000, v14
	v_lshlrev_b32_e32 v58, 16, v14
	v_pk_fma_f32 v[22:23], v[26:27], v[22:23], v[56:57] op_sel_hi:[0,1,1]
	v_pk_mul_f32 v[54:55], v[54:55], v[58:59]
	v_pk_fma_f32 v[22:23], v[0:1], v[32:33], v[22:23] op_sel_hi:[0,1,1]
	v_cvt_pk_bf16_f32 v14, v54, v55
	v_and_b32_e32 v55, 0xffff0000, v25
	v_lshlrev_b32_e32 v54, 16, v25
	v_pk_add_f32 v[22:23], v[40:41], v[22:23] op_sel_hi:[0,1]
	v_and_b32_e32 v25, 0xffff0000, v15
	v_lshlrev_b32_e32 v24, 16, v15
	v_pk_mul_f32 v[22:23], v[22:23], v[54:55]
	v_pk_mov_b32 v[56:57], v[32:33], v[28:29] op_sel:[1,0]
	v_pk_mul_f32 v[22:23], v[22:23], v[24:25]
	v_pk_mul_f32 v[56:57], v[38:39], v[56:57] op_sel_hi:[0,1]
	v_cvt_pk_bf16_f32 v15, v22, v23
	ds_read2_b32 v[22:23], v27 offset1:1
	v_pk_fma_f32 v[32:33], v[26:27], v[32:33], v[56:57] op_sel_hi:[0,1,1]
	v_pk_fma_f32 v[32:33], v[0:1], v[28:29], v[32:33] op_sel_hi:[0,1,1]
	v_pk_add_f32 v[32:33], v[40:41], v[32:33] op_sel_hi:[0,1]
	v_and_b32_e32 v55, 0xffff0000, v16
	s_waitcnt lgkmcnt(0)
	v_and_b32_e32 v25, 0xffff0000, v22
	v_lshlrev_b32_e32 v24, 16, v22
	v_lshlrev_b32_e32 v54, 16, v16
	v_pk_mul_f32 v[24:25], v[32:33], v[24:25]
	v_mov_b32_e32 v30, v29
	v_pk_mul_f32 v[24:25], v[24:25], v[54:55]
	v_mov_b32_e32 v52, v31
	v_cvt_pk_bf16_f32 v16, v24, v25
	v_pk_mul_f32 v[24:25], v[38:39], v[30:31] op_sel_hi:[0,1]
	v_pk_fma_f32 v[24:25], v[26:27], v[28:29], v[24:25] op_sel_hi:[0,1,1]
	v_pk_fma_f32 v[24:25], v[0:1], v[52:53], v[24:25] op_sel_hi:[0,1,1]
	v_pk_add_f32 v[24:25], v[40:41], v[24:25] op_sel_hi:[0,1]
	v_and_b32_e32 v29, 0xffff0000, v23
	v_lshlrev_b32_e32 v28, 16, v23
	v_pk_mul_f32 v[22:23], v[24:25], v[28:29]
	v_and_b32_e32 v25, 0xffff0000, v17
	v_lshlrev_b32_e32 v24, 16, v17
	v_pk_mul_f32 v[22:23], v[22:23], v[24:25]
	s_waitcnt vmcnt(4)
	v_lshlrev_b32_e32 v25, 16, v20
	v_cvt_pk_bf16_f32 v17, v22, v23
	global_store_dwordx4 v[48:49], v[14:17], off
	v_and_b32_e32 v23, 0xffff0000, v21
	v_and_b32_e32 v24, 0xffff0000, v19
	v_ashrrev_i32_e32 v16, 4, v69
	v_lshlrev_b32_e32 v16, 1, v16
	v_mul_lo_u32 v15, v68, s0
	v_and_b32_e32 v16, -4, v16
	v_add3_u32 v15, v15, v73, v16
	v_add_u32_e32 v27, 0x480, v15
	v_lshlrev_b32_e32 v14, 16, v18
	v_and_b32_e32 v16, 0xffff0000, v20
	v_lshlrev_b32_e32 v17, 16, v21
	v_and_b32_e32 v18, 0xffff0000, v18
	ds_read2_b32 v[20:21], v27 offset1:1
	v_mov_b32_e32 v50, v18
	v_pk_mul_f32 v[32:33], v[38:39], v[50:51]
	v_add_u32_e32 v36, 0x488, v15
	v_lshlrev_b32_e32 v19, 16, v19
	v_pk_fma_f32 v[14:15], v[38:39], v[14:15], v[32:33] op_sel:[0,0,1] op_sel_hi:[1,0,0]
	s_waitcnt lgkmcnt(0)
	v_and_b32_e32 v29, 0xffff0000, v20
	v_pk_fma_f32 v[14:15], v[0:1], v[18:19], v[14:15] op_sel_hi:[0,1,1]
	v_lshlrev_b32_e32 v28, 16, v20
	v_pk_add_f32 v[14:15], v[40:41], v[14:15] op_sel_hi:[0,1]
	v_pk_mul_f32 v[14:15], v[14:15], v[28:29]
	v_pk_mov_b32 v[28:29], v[18:19], v[24:25] op_sel:[1,0]
	s_waitcnt vmcnt(4)
	v_and_b32_e32 v31, 0xffff0000, v10
	v_pk_mul_f32 v[28:29], v[38:39], v[28:29] op_sel_hi:[0,1]
	v_lshlrev_b32_e32 v30, 16, v10
	v_pk_fma_f32 v[18:19], v[26:27], v[18:19], v[28:29] op_sel_hi:[0,1,1]
	v_pk_mul_f32 v[14:15], v[14:15], v[30:31]
	v_pk_fma_f32 v[18:19], v[0:1], v[24:25], v[18:19] op_sel_hi:[0,1,1]
	v_cvt_pk_bf16_f32 v10, v14, v15
	v_and_b32_e32 v15, 0xffff0000, v21
	v_lshlrev_b32_e32 v14, 16, v21
	v_pk_add_f32 v[18:19], v[40:41], v[18:19] op_sel_hi:[0,1]
	v_and_b32_e32 v21, 0xffff0000, v11
	v_lshlrev_b32_e32 v20, 16, v11
	v_pk_mul_f32 v[14:15], v[18:19], v[14:15]
	v_pk_mov_b32 v[28:29], v[24:25], v[16:17] op_sel:[1,0]
	v_pk_mul_f32 v[14:15], v[14:15], v[20:21]
	v_pk_mul_f32 v[28:29], v[38:39], v[28:29] op_sel_hi:[0,1]
	v_cvt_pk_bf16_f32 v11, v14, v15
	ds_read2_b32 v[14:15], v36 offset1:1
	v_pk_fma_f32 v[24:25], v[26:27], v[24:25], v[28:29] op_sel_hi:[0,1,1]
	v_pk_fma_f32 v[24:25], v[0:1], v[16:17], v[24:25] op_sel_hi:[0,1,1]
	v_pk_add_f32 v[24:25], v[40:41], v[24:25] op_sel_hi:[0,1]
	v_and_b32_e32 v21, 0xffff0000, v12
	s_waitcnt lgkmcnt(0)
	v_and_b32_e32 v19, 0xffff0000, v14
	v_lshlrev_b32_e32 v18, 16, v14
	v_lshlrev_b32_e32 v20, 16, v12
	v_pk_mul_f32 v[18:19], v[24:25], v[18:19]
	v_mov_b32_e32 v22, v17
	v_pk_mul_f32 v[18:19], v[18:19], v[20:21]
	v_mov_b32_e32 v46, v23
	v_cvt_pk_bf16_f32 v12, v18, v19
	v_pk_mul_f32 v[18:19], v[38:39], v[22:23] op_sel_hi:[0,1]
	v_pk_fma_f32 v[16:17], v[26:27], v[16:17], v[18:19] op_sel_hi:[0,1,1]
	v_pk_fma_f32 v[16:17], v[0:1], v[46:47], v[16:17] op_sel_hi:[0,1,1]
	v_pk_add_f32 v[16:17], v[40:41], v[16:17] op_sel_hi:[0,1]
	v_and_b32_e32 v19, 0xffff0000, v15
	v_lshlrev_b32_e32 v18, 16, v15
	v_pk_mul_f32 v[14:15], v[16:17], v[18:19]
	v_and_b32_e32 v17, 0xffff0000, v13
	v_lshlrev_b32_e32 v16, 16, v13
	v_pk_mul_f32 v[14:15], v[14:15], v[16:17]
	s_waitcnt vmcnt(3)
	v_lshlrev_b32_e32 v16, 16, v6
	v_cvt_pk_bf16_f32 v13, v14, v15
	global_store_dwordx4 v[44:45], v[10:13], off
	v_lshlrev_b32_e32 v15, 16, v8
	v_and_b32_e32 v6, 0xffff0000, v6
	v_ashrrev_i32_e32 v11, 4, v75
	v_lshlrev_b32_e32 v11, 1, v11
	v_mul_lo_u32 v10, v74, s0
	v_and_b32_e32 v11, -4, v11
	v_add3_u32 v10, v10, v77, v11
	v_add_u32_e32 v17, 0x480, v10
	v_add_u32_e32 v24, 0x488, v10
	v_and_b32_e32 v10, 0xffff0000, v8
	v_lshlrev_b32_e32 v11, 16, v9
	v_and_b32_e32 v13, 0xffff0000, v9
	ds_read2_b32 v[8:9], v17 offset1:1
	v_mov_b32_e32 v42, v6
	v_pk_mul_f32 v[22:23], v[38:39], v[42:43]
	v_and_b32_e32 v14, 0xffff0000, v7
	v_lshlrev_b32_e32 v7, 16, v7
	v_pk_fma_f32 v[16:17], v[38:39], v[16:17], v[22:23] op_sel:[0,0,1] op_sel_hi:[1,0,0]
	s_waitcnt lgkmcnt(0)
	v_and_b32_e32 v19, 0xffff0000, v8
	v_pk_fma_f32 v[16:17], v[0:1], v[6:7], v[16:17] op_sel_hi:[0,1,1]
	v_lshlrev_b32_e32 v18, 16, v8
	v_pk_add_f32 v[16:17], v[40:41], v[16:17] op_sel_hi:[0,1]
	v_pk_mul_f32 v[16:17], v[16:17], v[18:19]
	v_pk_mov_b32 v[18:19], v[6:7], v[14:15] op_sel:[1,0]
	s_waitcnt vmcnt(3)
	v_and_b32_e32 v21, 0xffff0000, v2
	v_pk_mul_f32 v[18:19], v[38:39], v[18:19] op_sel_hi:[0,1]
	v_lshlrev_b32_e32 v20, 16, v2
	v_pk_fma_f32 v[6:7], v[26:27], v[6:7], v[18:19] op_sel_hi:[0,1,1]
	v_pk_mul_f32 v[16:17], v[16:17], v[20:21]
	v_pk_fma_f32 v[6:7], v[0:1], v[14:15], v[6:7] op_sel_hi:[0,1,1]
	v_cvt_pk_bf16_f32 v2, v16, v17
	v_and_b32_e32 v17, 0xffff0000, v9
	v_lshlrev_b32_e32 v16, 16, v9
	v_pk_add_f32 v[6:7], v[40:41], v[6:7] op_sel_hi:[0,1]
	v_and_b32_e32 v9, 0xffff0000, v3
	v_lshlrev_b32_e32 v8, 16, v3
	v_pk_mul_f32 v[6:7], v[6:7], v[16:17]
	v_pk_mov_b32 v[18:19], v[14:15], v[10:11] op_sel:[1,0]
	v_pk_mul_f32 v[6:7], v[6:7], v[8:9]
	v_pk_mul_f32 v[18:19], v[38:39], v[18:19] op_sel_hi:[0,1]
	v_cvt_pk_bf16_f32 v3, v6, v7
	ds_read2_b32 v[6:7], v24 offset1:1
	v_pk_fma_f32 v[14:15], v[26:27], v[14:15], v[18:19] op_sel_hi:[0,1,1]
	v_pk_fma_f32 v[14:15], v[0:1], v[10:11], v[14:15] op_sel_hi:[0,1,1]
	v_pk_add_f32 v[14:15], v[40:41], v[14:15] op_sel_hi:[0,1]
	v_and_b32_e32 v17, 0xffff0000, v4
	s_waitcnt lgkmcnt(0)
	v_and_b32_e32 v9, 0xffff0000, v6
	v_lshlrev_b32_e32 v8, 16, v6
	v_lshlrev_b32_e32 v16, 16, v4
	v_pk_mul_f32 v[8:9], v[14:15], v[8:9]
	v_mov_b32_e32 v12, v11
	v_pk_mul_f32 v[8:9], v[8:9], v[16:17]
	v_mov_b32_e32 v36, v13
	v_cvt_pk_bf16_f32 v4, v8, v9
	v_pk_mul_f32 v[8:9], v[38:39], v[12:13] op_sel_hi:[0,1]
	v_pk_fma_f32 v[8:9], v[26:27], v[10:11], v[8:9] op_sel_hi:[0,1,1]
	v_pk_fma_f32 v[8:9], v[0:1], v[36:37], v[8:9] op_sel_hi:[0,1,1]
	v_pk_add_f32 v[8:9], v[40:41], v[8:9] op_sel_hi:[0,1]
	v_and_b32_e32 v11, 0xffff0000, v7
	v_lshlrev_b32_e32 v10, 16, v7
	v_pk_mul_f32 v[6:7], v[8:9], v[10:11]
	v_and_b32_e32 v9, 0xffff0000, v5
	v_lshlrev_b32_e32 v8, 16, v5
	v_pk_mul_f32 v[6:7], v[6:7], v[8:9]
	s_mov_b64 s[0:1], 0
	v_cvt_pk_bf16_f32 v5, v6, v7
	global_store_dwordx4 v[34:35], v[2:5], off

.LBB0_553:
	s_or_b64 exec, exec, s[28:29]
	v_cmp_gt_i32_e32 vcc, 33, v111
	s_and_saveexec_b64 s[28:29], vcc
	v_add_u32_e32 v2, 0x2000, v111
	v_cmp_ne_u32_e32 vcc, 32, v111
	s_nop 1
	v_cndmask_b32_e32 v2, 0, v2, vcc
	v_lshlrev_b32_e32 v2, 1, v2
	ds_write_b16 v2, v1
	s_or_b64 exec, exec, s[28:29]
	s_lshl_b64 s[4:5], s[50:51], 2
	s_add_u32 s6, s86, s4
	s_addc_u32 s7, s87, s5
	s_add_u32 s4, s90, s4
	s_addc_u32 s5, s78, s5
	v_mov_b32_e32 v2, 0x1000
	v_mov_b32_e32 v3, 0x2000
	s_or_b32 s1, s50, 0x200
	global_load_dword v21, v1, s[6:7] offset:1024
	global_load_dword v20, v2, s[6:7]
	global_load_dword v12, v2, s[6:7] offset:3072
	global_load_dword v19, v1, s[6:7] offset:2048
	global_load_dword v18, v2, s[6:7] offset:1024
	global_load_dword v10, v3, s[6:7]
	global_load_dword v113, v1, s[6:7]
	global_load_dword v110, v2, s[6:7] offset:2048
	global_load_dword v16, v1, s[4:5] offset:1024
	global_load_dword v14, v1, s[4:5] offset:2048
	global_load_dword v112, v1, s[6:7] offset:3072
	global_load_dword v114, v1, s[4:5]
	s_mul_hi_u32 s4, s0, 0xc000
	s_mul_i32 s0, s0, 0xc000
	v_readlane_b32 s5, v253, 40
	s_add_u32 s0, s5, s0
	v_readlane_b32 s6, v253, 41
	s_addc_u32 s4, s6, s4
	s_add_u32 s28, s0, 0x4000
	s_addc_u32 s29, s4, 0
	s_mul_hi_u32 s0, s1, 0xc000
	s_mul_i32 s1, s1, 0xc000
	s_add_u32 s1, s5, s1
	s_addc_u32 s0, s6, s0
	s_add_u32 s38, s1, 0x4000
	v_lshlrev_b64 v[122:123], 1, v[118:119]
	s_addc_u32 s39, s0, 0
	v_lshl_add_u64 v[24:25], s[28:29], 0, v[122:123]
	s_waitcnt vmcnt(22)
	v_lshl_add_u64 v[28:29], s[38:39], 0, v[122:123]
	global_load_dwordx4 v[6:9], v[24:25], off
	global_load_dwordx4 v[2:5], v[28:29], off
	v_ashrrev_i32_e32 v11, 31, v111
	v_lshrrev_b32_e32 v164, 23, v11
	v_add_u32_e32 v11, v111, v164
	v_ashrrev_i32_e32 v160, 9, v11
	v_lshlrev_b32_e32 v11, 12, v160
	v_sub_u32_e32 v161, v118, v11
	v_cmp_lt_i32_e32 vcc, 0, v161
	v_mov_b32_e32 v23, 0
	v_mov_b32_e32 v27, 0
	s_and_saveexec_b64 s[0:1], vcc
	s_cbranch_execz .LBB0_557
	global_load_ushort v27, v[24:25], off offset:-2
.LBB0_557:
	s_or_b64 exec, exec, s[0:1]
	s_movk_i32 s0, 0xff8
	v_cmp_gt_i32_e64 s[0:1], s0, v161
	s_and_saveexec_b64 s[40:41], s[0:1]
	s_cbranch_execz .LBB0_559
	global_load_ushort v23, v[24:25], off offset:16
.LBB0_559:
	s_or_b64 exec, exec, s[40:41]
	v_mov_b32_e32 v25, 0
	s_waitcnt vmcnt(23)
	v_mov_b32_e32 v31, 0
	s_and_saveexec_b64 s[40:41], vcc
	s_cbranch_execz .LBB0_561
	global_load_ushort v31, v[28:29], off offset:-2

.LBB0_563:
	s_or_b64 exec, exec, s[40:41]
	s_waitcnt vmcnt(0)
	v_lshlrev_b32_e32 v27, 16, v27
	v_lshlrev_b32_e32 v23, 16, v23
	v_lshlrev_b32_e32 v31, 16, v31
	v_lshlrev_b32_e32 v25, 16, v25
	v_lshlrev_b32_e32 v22, 16, v6
	v_lshlrev_b32_e32 v29, 16, v9
	v_and_b32_e32 v33, 0xffff0000, v9
	s_waitcnt vmcnt(0)
	v_and_b32_e32 v34, 0xffff0000, v4
	v_lshlrev_b32_e32 v9, 16, v4
	v_and_b32_e32 v4, 0xffff0000, v6
	v_and_b32_e32 v6, 0xffff0000, v2
	v_mov_b32_e32 v26, v4
	v_mov_b32_e32 v30, v6
	v_lshlrev_b32_e32 v24, 16, v2
	v_and_b32_e32 v28, 0xffff0000, v8
	v_lshlrev_b32_e32 v35, 16, v5
	v_and_b32_e32 v37, 0xffff0000, v5
	v_and_b32_e32 v38, 0xffff0000, v7
	v_lshlrev_b32_e32 v39, 16, v8
	v_and_b32_e32 v8, 0xffff0000, v3
	v_lshlrev_b32_e32 v5, 16, v7
	v_lshlrev_b32_e32 v7, 16, v3
	v_pk_mul_f32 v[2:3], v[20:21], v[26:27]
	v_pk_mul_f32 v[26:27], v[18:19], v[30:31]
	v_pk_fma_f32 v[2:3], v[20:21], v[22:23], v[2:3] op_sel:[0,0,1] op_sel_hi:[1,0,0]
	v_pk_fma_f32 v[26:27], v[18:19], v[24:25], v[26:27] op_sel:[0,0,1] op_sel_hi:[1,0,0]
	v_pk_fma_f32 v[2:3], v[12:13], v[4:5], v[2:3] op_sel_hi:[0,1,1]
	v_pk_fma_f32 v[26:27], v[10:11], v[6:7], v[26:27] op_sel_hi:[0,1,1]
	v_pk_add_f32 v[2:3], v[16:17], v[2:3] op_sel_hi:[0,1]
	v_pk_add_f32 v[26:27], v[14:15], v[26:27] op_sel_hi:[0,1]
	v_pk_mul_f32 v[2:3], v[2:3], v[26:27]
	v_pk_mov_b32 v[26:27], v[4:5], v[38:39] op_sel:[1,0]
	v_mov_b32_e32 v22, v21
	v_pk_mul_f32 v[26:27], v[20:21], v[26:27] op_sel_hi:[0,1]
	v_pk_fma_f32 v[4:5], v[22:23], v[4:5], v[26:27] op_sel_hi:[0,1,1]
	v_pk_mov_b32 v[26:27], v[6:7], v[8:9] op_sel:[1,0]
	v_mov_b32_e32 v24, v19
	v_pk_mul_f32 v[26:27], v[18:19], v[26:27] op_sel_hi:[0,1]
	v_pk_fma_f32 v[6:7], v[24:25], v[6:7], v[26:27] op_sel_hi:[0,1,1]
	v_pk_fma_f32 v[4:5], v[12:13], v[38:39], v[4:5] op_sel_hi:[0,1,1]
	v_pk_fma_f32 v[6:7], v[10:11], v[8:9], v[6:7] op_sel_hi:[0,1,1]
	v_pk_add_f32 v[4:5], v[16:17], v[4:5] op_sel_hi:[0,1]
	v_pk_add_f32 v[6:7], v[14:15], v[6:7] op_sel_hi:[0,1]
	v_pk_mul_f32 v[4:5], v[4:5], v[6:7]
	v_cvt_pk_bf16_f32 v2, v2, v3
	v_cvt_pk_bf16_f32 v3, v4, v5
	v_pk_mov_b32 v[4:5], v[38:39], v[28:29] op_sel:[1,0]
	v_pk_mov_b32 v[6:7], v[8:9], v[34:35] op_sel:[1,0]
	v_pk_mul_f32 v[4:5], v[20:21], v[4:5] op_sel_hi:[0,1]
	v_pk_mul_f32 v[6:7], v[18:19], v[6:7] op_sel_hi:[0,1]
	v_pk_fma_f32 v[4:5], v[22:23], v[38:39], v[4:5] op_sel_hi:[0,1,1]
	v_pk_fma_f32 v[6:7], v[24:25], v[8:9], v[6:7] op_sel_hi:[0,1,1]
	v_pk_fma_f32 v[4:5], v[12:13], v[28:29], v[4:5] op_sel_hi:[0,1,1]
	v_pk_fma_f32 v[6:7], v[10:11], v[34:35], v[6:7] op_sel_hi:[0,1,1]
	v_mov_b32_e32 v32, v29
	v_mov_b32_e32 v36, v35
	v_pk_add_f32 v[4:5], v[16:17], v[4:5] op_sel_hi:[0,1]
	v_pk_add_f32 v[6:7], v[14:15], v[6:7] op_sel_hi:[0,1]
	v_pk_mul_f32 v[4:5], v[4:5], v[6:7]
	v_pk_mul_f32 v[6:7], v[20:21], v[32:33] op_sel_hi:[0,1]
	v_pk_mul_f32 v[8:9], v[18:19], v[36:37] op_sel_hi:[0,1]
	v_pk_fma_f32 v[6:7], v[22:23], v[28:29], v[6:7] op_sel_hi:[0,1,1]
	v_mov_b32_e32 v22, v33
	v_pk_fma_f32 v[8:9], v[24:25], v[34:35], v[8:9] op_sel_hi:[0,1,1]
	v_mov_b32_e32 v24, v37
	v_pk_fma_f32 v[6:7], v[12:13], v[22:23], v[6:7] op_sel_hi:[0,1,1]
	v_pk_fma_f32 v[8:9], v[10:11], v[24:25], v[8:9] op_sel_hi:[0,1,1]
	v_pk_add_f32 v[6:7], v[16:17], v[6:7] op_sel_hi:[0,1]
	v_pk_add_f32 v[8:9], v[14:15], v[8:9] op_sel_hi:[0,1]
	v_pk_mul_f32 v[6:7], v[6:7], v[8:9]
	v_cvt_pk_bf16_f32 v4, v4, v5
	v_cvt_pk_bf16_f32 v5, v6, v7
	v_add_u32_e32 v6, 0x400, v161
	v_ashrrev_i32_e32 v6, 1, v6
	v_mul_i32_i24_e32 v7, 0x3c00, v160
	v_lshlrev_b32_e32 v162, 1, v161
	v_and_b32_e32 v6, -16, v6
	v_add3_u32 v6, v7, v162, v6
	ds_write_b128 v6, v[2:5] offset:18560
	v_ashrrev_i32_e32 v2, 31, v115
	v_lshrrev_b32_e32 v166, 23, v2
	v_add_u32_e32 v2, v115, v166
	v_ashrrev_i32_e32 v155, 9, v2
	v_lshlrev_b64 v[126:127], 1, v[116:117]
	v_lshlrev_b32_e32 v2, 12, v155
	v_lshl_add_u64 v[24:25], s[28:29], 0, v[126:127]
	v_lshl_add_u64 v[22:23], s[38:39], 0, v[126:127]
	v_sub_u32_e32 v158, v116, v2
	global_load_dwordx4 v[2:5], v[24:25], off
	global_load_dwordx4 v[6:9], v[22:23], off
	v_cmp_lt_i32_e32 vcc, 0, v158
	v_mov_b32_e32 v31, 0
	v_mov_b32_e32 v35, 0
	s_and_saveexec_b64 s[0:1], vcc
	s_cbranch_execz .LBB0_565
	global_load_ushort v35, v[24:25], off offset:-2
.LBB0_565:
	s_or_b64 exec, exec, s[0:1]
	s_movk_i32 s0, 0xff8
	v_cmp_gt_i32_e64 s[0:1], s0, v158
	s_and_saveexec_b64 s[40:41], s[0:1]
	s_cbranch_execz .LBB0_567
	global_load_ushort v31, v[24:25], off offset:16

.LBB0_571:
	s_or_b64 exec, exec, s[40:41]
	s_waitcnt vmcnt(0)
	v_lshlrev_b32_e32 v35, 16, v35
	v_lshlrev_b32_e32 v31, 16, v31
	v_lshlrev_b32_e32 v37, 16, v37
	v_lshlrev_b32_e32 v33, 16, v33
	v_lshlrev_b32_e32 v32, 16, v6
	v_lshlrev_b32_e32 v39, 16, v5
	v_and_b32_e32 v41, 0xffff0000, v5
	v_and_b32_e32 v42, 0xffff0000, v8
	v_lshlrev_b32_e32 v5, 16, v8
	v_and_b32_e32 v8, 0xffff0000, v2
	v_and_b32_e32 v6, 0xffff0000, v6
	v_mov_b32_e32 v34, v8
	v_mov_b32_e32 v36, v6
	v_lshlrev_b32_e32 v30, 16, v2
	v_lshlrev_b32_e32 v43, 16, v9
	v_and_b32_e32 v45, 0xffff0000, v9
	v_and_b32_e32 v46, 0xffff0000, v3
	v_lshlrev_b32_e32 v9, 16, v3
	v_pk_mul_f32 v[2:3], v[20:21], v[34:35]
	v_pk_mul_f32 v[34:35], v[18:19], v[36:37]
	v_mov_b32_e32 v13, v12
	v_mov_b32_e32 v11, v10
	v_and_b32_e32 v38, 0xffff0000, v4
	v_lshlrev_b32_e32 v47, 16, v4
	v_and_b32_e32 v4, 0xffff0000, v7
	v_lshlrev_b32_e32 v7, 16, v7
	v_pk_fma_f32 v[2:3], v[20:21], v[30:31], v[2:3] op_sel:[0,0,1] op_sel_hi:[1,0,0]
	v_pk_fma_f32 v[34:35], v[18:19], v[32:33], v[34:35] op_sel:[0,0,1] op_sel_hi:[1,0,0]
	v_mov_b32_e32 v17, v16
	v_mov_b32_e32 v15, v14
	v_pk_fma_f32 v[2:3], v[12:13], v[8:9], v[2:3]
	v_pk_fma_f32 v[34:35], v[10:11], v[6:7], v[34:35]
	v_pk_add_f32 v[2:3], v[16:17], v[2:3]
	v_pk_add_f32 v[34:35], v[14:15], v[34:35]
	v_mov_b32_e32 v28, v20
	v_mov_b32_e32 v29, v20
	v_pk_mul_f32 v[2:3], v[2:3], v[34:35]
	v_pk_mov_b32 v[34:35], v[8:9], v[46:47] op_sel:[1,0]
	v_mov_b32_e32 v24, v21
	v_mov_b32_e32 v25, v21
	v_pk_mul_f32 v[34:35], v[28:29], v[34:35]
	v_mov_b32_e32 v26, v18
	v_mov_b32_e32 v27, v18
	v_pk_fma_f32 v[8:9], v[24:25], v[8:9], v[34:35]
	v_pk_mov_b32 v[34:35], v[6:7], v[4:5] op_sel:[1,0]
	v_mov_b32_e32 v22, v19
	v_mov_b32_e32 v23, v19
	v_pk_mul_f32 v[34:35], v[26:27], v[34:35]
	v_pk_fma_f32 v[8:9], v[12:13], v[46:47], v[8:9]
	v_pk_fma_f32 v[6:7], v[22:23], v[6:7], v[34:35]
	v_pk_add_f32 v[8:9], v[16:17], v[8:9]
	v_pk_fma_f32 v[6:7], v[10:11], v[4:5], v[6:7]
	v_cvt_pk_bf16_f32 v2, v2, v3
	v_pk_add_f32 v[6:7], v[14:15], v[6:7]
	v_mov_b32_e32 v40, v39
	v_pk_mul_f32 v[6:7], v[8:9], v[6:7]
	v_pk_mov_b32 v[8:9], v[4:5], v[42:43] op_sel:[1,0]
	v_cvt_pk_bf16_f32 v3, v6, v7
	v_pk_mov_b32 v[6:7], v[46:47], v[38:39] op_sel:[1,0]
	v_pk_mul_f32 v[8:9], v[26:27], v[8:9]
	v_pk_mul_f32 v[6:7], v[28:29], v[6:7]
	v_pk_fma_f32 v[4:5], v[22:23], v[4:5], v[8:9]
	v_pk_fma_f32 v[6:7], v[24:25], v[46:47], v[6:7]
	v_pk_fma_f32 v[4:5], v[10:11], v[42:43], v[4:5]
	v_pk_fma_f32 v[6:7], v[12:13], v[38:39], v[6:7]
	v_mov_b32_e32 v44, v43
	v_pk_add_f32 v[6:7], v[16:17], v[6:7]
	v_pk_add_f32 v[4:5], v[14:15], v[4:5]
	v_pk_mul_f32 v[8:9], v[26:27], v[44:45]
	v_pk_mul_f32 v[4:5], v[6:7], v[4:5]
	v_pk_mul_f32 v[6:7], v[28:29], v[40:41]
	v_mov_b32_e32 v30, v41
	v_pk_fma_f32 v[6:7], v[24:25], v[38:39], v[6:7]
	v_pk_fma_f32 v[8:9], v[22:23], v[42:43], v[8:9]
	v_mov_b32_e32 v32, v45
	v_pk_fma_f32 v[6:7], v[12:13], v[30:31], v[6:7]
	v_pk_fma_f32 v[8:9], v[10:11], v[32:33], v[8:9]
	v_pk_add_f32 v[6:7], v[16:17], v[6:7]
	v_pk_add_f32 v[8:9], v[14:15], v[8:9]
	v_cvt_pk_bf16_f32 v4, v4, v5
	v_pk_mul_f32 v[6:7], v[6:7], v[8:9]
	v_lshlrev_b32_e32 v167, 1, v158
	v_cvt_pk_bf16_f32 v5, v6, v7
	v_add_u32_e32 v6, 0x400, v158
	v_ashrrev_i32_e32 v6, 1, v6
	v_mul_i32_i24_e32 v7, 0x3c00, v155
	v_and_b32_e32 v6, -16, v6
	v_add3_u32 v6, v7, v167, v6
	v_add_u32_e32 v174, 0x200, v111
	ds_write_b128 v6, v[2:5] offset:18560
	v_ashrrev_i32_e32 v2, 31, v174
	v_lshrrev_b32_e32 v175, 23, v2
	v_lshlrev_b32_e32 v120, 3, v174
	v_add_u32_e32 v2, v174, v175
	v_ashrrev_i32_e32 v121, 31, v120
	v_ashrrev_i32_e32 v163, 9, v2
	v_lshlrev_b64 v[132:133], 1, v[120:121]
	v_lshlrev_b32_e32 v2, 12, v163
	v_lshl_add_u64 v[32:33], s[28:29], 0, v[132:133]
	v_lshl_add_u64 v[30:31], s[38:39], 0, v[132:133]
	v_sub_u32_e32 v165, v120, v2
	global_load_dwordx4 v[2:5], v[32:33], off
	global_load_dwordx4 v[6:9], v[30:31], off
	v_cmp_lt_i32_e32 vcc, 0, v165
	v_mov_b32_e32 v35, 0
	v_mov_b32_e32 v37, 0
	s_and_saveexec_b64 s[0:1], vcc
	s_cbranch_execz .LBB0_573
	global_load_ushort v37, v[32:33], off offset:-2
.LBB0_573:
	s_or_b64 exec, exec, s[0:1]
	s_movk_i32 s0, 0xff8
	v_cmp_gt_i32_e64 s[0:1], s0, v165
	s_and_saveexec_b64 s[40:41], s[0:1]
	s_cbranch_execz .LBB0_575
	global_load_ushort v35, v[32:33], off offset:16
.LBB0_575:
	s_or_b64 exec, exec, s[40:41]
	v_mov_b32_e32 v33, 0
	v_mov_b32_e32 v39, 0
	s_and_saveexec_b64 s[40:41], vcc
	s_cbranch_execz .LBB0_577
	global_load_ushort v39, v[30:31], off offset:-2

.LBB0_579:
	s_or_b64 exec, exec, s[40:41]
	s_waitcnt vmcnt(0)
	v_lshlrev_b32_e32 v37, 16, v37
	v_lshlrev_b32_e32 v35, 16, v35
	v_lshlrev_b32_e32 v39, 16, v39
	v_lshlrev_b32_e32 v33, 16, v33
	v_lshlrev_b32_e32 v41, 16, v5
	v_and_b32_e32 v43, 0xffff0000, v5
	s_waitcnt vmcnt(0)
	v_and_b32_e32 v44, 0xffff0000, v8
	v_lshlrev_b32_e32 v5, 16, v8
	v_and_b32_e32 v8, 0xffff0000, v2
	v_lshlrev_b32_e32 v32, 16, v6
	v_and_b32_e32 v6, 0xffff0000, v6
	v_mov_b32_e32 v36, v8
	v_lshlrev_b32_e32 v30, 16, v2
	v_lshlrev_b32_e32 v45, 16, v9
	v_and_b32_e32 v47, 0xffff0000, v9
	v_and_b32_e32 v48, 0xffff0000, v3
	v_lshlrev_b32_e32 v9, 16, v3
	v_pk_mul_f32 v[2:3], v[20:21], v[36:37]
	v_mov_b32_e32 v38, v6
	v_pk_fma_f32 v[2:3], v[20:21], v[30:31], v[2:3] op_sel:[0,0,1] op_sel_hi:[1,0,0]
	v_pk_mul_f32 v[30:31], v[18:19], v[38:39]
	v_and_b32_e32 v40, 0xffff0000, v4
	v_lshlrev_b32_e32 v49, 16, v4
	v_and_b32_e32 v4, 0xffff0000, v7
	v_lshlrev_b32_e32 v7, 16, v7
	v_pk_fma_f32 v[30:31], v[18:19], v[32:33], v[30:31] op_sel:[0,0,1] op_sel_hi:[1,0,0]
	v_pk_fma_f32 v[2:3], v[12:13], v[8:9], v[2:3]
	v_pk_fma_f32 v[30:31], v[10:11], v[6:7], v[30:31]
	v_pk_add_f32 v[2:3], v[16:17], v[2:3]
	v_pk_add_f32 v[30:31], v[14:15], v[30:31]
	v_mov_b32_e32 v42, v41
	v_pk_mul_f32 v[2:3], v[2:3], v[30:31]
	v_pk_mov_b32 v[30:31], v[8:9], v[48:49] op_sel:[1,0]
	v_cvt_pk_bf16_f32 v2, v2, v3
	v_pk_mul_f32 v[30:31], v[28:29], v[30:31]
	v_mov_b32_e32 v46, v45
	v_pk_fma_f32 v[8:9], v[24:25], v[8:9], v[30:31]
	v_pk_mov_b32 v[30:31], v[6:7], v[4:5] op_sel:[1,0]
	v_pk_fma_f32 v[8:9], v[12:13], v[48:49], v[8:9]
	v_pk_mul_f32 v[30:31], v[26:27], v[30:31]
	v_pk_add_f32 v[8:9], v[16:17], v[8:9]
	v_pk_fma_f32 v[6:7], v[22:23], v[6:7], v[30:31]
	v_mov_b32_e32 v34, v43
	v_pk_fma_f32 v[6:7], v[10:11], v[4:5], v[6:7]
	v_mov_b32_e32 v32, v47
	v_pk_add_f32 v[6:7], v[14:15], v[6:7]
	v_lshlrev_b32_e32 v168, 1, v165
	v_pk_mul_f32 v[6:7], v[8:9], v[6:7]
	v_pk_mov_b32 v[8:9], v[4:5], v[44:45] op_sel:[1,0]
	v_cvt_pk_bf16_f32 v3, v6, v7
	v_pk_mov_b32 v[6:7], v[48:49], v[40:41] op_sel:[1,0]
	v_pk_mul_f32 v[8:9], v[26:27], v[8:9]
	v_pk_mul_f32 v[6:7], v[28:29], v[6:7]
	v_pk_fma_f32 v[4:5], v[22:23], v[4:5], v[8:9]
	v_pk_fma_f32 v[6:7], v[24:25], v[48:49], v[6:7]
	v_pk_fma_f32 v[4:5], v[10:11], v[44:45], v[4:5]
	v_pk_fma_f32 v[6:7], v[12:13], v[40:41], v[6:7]
	v_pk_add_f32 v[4:5], v[14:15], v[4:5]
	v_pk_add_f32 v[6:7], v[16:17], v[6:7]
	v_pk_mul_f32 v[8:9], v[26:27], v[46:47]
	v_pk_mul_f32 v[4:5], v[6:7], v[4:5]
	v_pk_mul_f32 v[6:7], v[28:29], v[42:43]
	v_pk_fma_f32 v[8:9], v[22:23], v[44:45], v[8:9]
	v_pk_fma_f32 v[6:7], v[24:25], v[40:41], v[6:7]
	v_pk_fma_f32 v[8:9], v[10:11], v[32:33], v[8:9]
	v_pk_fma_f32 v[6:7], v[12:13], v[34:35], v[6:7]
	v_pk_add_f32 v[8:9], v[14:15], v[8:9]
	v_pk_add_f32 v[6:7], v[16:17], v[6:7]
	v_cvt_pk_bf16_f32 v4, v4, v5
	v_pk_mul_f32 v[6:7], v[6:7], v[8:9]
	v_add_u32_e32 v219, 0x300, v111
	v_cvt_pk_bf16_f32 v5, v6, v7
	v_add_u32_e32 v6, 0x400, v165
	v_ashrrev_i32_e32 v6, 1, v6
	v_mul_i32_i24_e32 v7, 0x3c00, v163
	v_and_b32_e32 v6, -16, v6
	v_add3_u32 v6, v7, v168, v6
	ds_write_b128 v6, v[2:5] offset:18560
	v_ashrrev_i32_e32 v2, 31, v219
	v_lshrrev_b32_e32 v220, 23, v2
	v_lshlrev_b32_e32 v124, 3, v219
	v_add_u32_e32 v2, v219, v220
	v_ashrrev_i32_e32 v125, 31, v124
	v_ashrrev_i32_e32 v169, 9, v2
	v_lshlrev_b64 v[138:139], 1, v[124:125]
	v_lshlrev_b32_e32 v2, 12, v169
	v_lshl_add_u64 v[32:33], s[28:29], 0, v[138:139]
	v_lshl_add_u64 v[30:31], s[38:39], 0, v[138:139]
	v_sub_u32_e32 v170, v124, v2
	global_load_dwordx4 v[2:5], v[32:33], off
	global_load_dwordx4 v[6:9], v[30:31], off
	v_cmp_lt_i32_e32 vcc, 0, v170
	v_mov_b32_e32 v35, 0
	v_mov_b32_e32 v37, 0
	s_and_saveexec_b64 s[0:1], vcc
	s_cbranch_execz .LBB0_581
	global_load_ushort v37, v[32:33], off offset:-2
.LBB0_581:
	s_or_b64 exec, exec, s[0:1]
	s_movk_i32 s0, 0xff8
	v_cmp_gt_i32_e64 s[0:1], s0, v170
	s_and_saveexec_b64 s[40:41], s[0:1]
	s_cbranch_execz .LBB0_583
	global_load_ushort v35, v[32:33], off offset:16

.LBB0_587:
	s_or_b64 exec, exec, s[40:41]
	s_waitcnt vmcnt(0)
	v_lshlrev_b32_e32 v37, 16, v37
	v_lshlrev_b32_e32 v35, 16, v35
	v_lshlrev_b32_e32 v39, 16, v39
	v_lshlrev_b32_e32 v33, 16, v33
	v_lshlrev_b32_e32 v41, 16, v5
	v_and_b32_e32 v43, 0xffff0000, v5
	s_waitcnt vmcnt(0)
	v_and_b32_e32 v44, 0xffff0000, v8
	v_lshlrev_b32_e32 v5, 16, v8
	v_and_b32_e32 v8, 0xffff0000, v2
	v_lshlrev_b32_e32 v32, 16, v6
	v_and_b32_e32 v6, 0xffff0000, v6
	v_mov_b32_e32 v36, v8
	v_lshlrev_b32_e32 v30, 16, v2
	v_lshlrev_b32_e32 v45, 16, v9
	v_and_b32_e32 v47, 0xffff0000, v9
	v_and_b32_e32 v48, 0xffff0000, v3
	v_lshlrev_b32_e32 v9, 16, v3
	v_pk_mul_f32 v[2:3], v[20:21], v[36:37]
	v_mov_b32_e32 v38, v6
	v_pk_fma_f32 v[2:3], v[20:21], v[30:31], v[2:3] op_sel:[0,0,1] op_sel_hi:[1,0,0]
	v_pk_mul_f32 v[30:31], v[18:19], v[38:39]
	v_and_b32_e32 v40, 0xffff0000, v4
	v_lshlrev_b32_e32 v49, 16, v4
	v_and_b32_e32 v4, 0xffff0000, v7
	v_lshlrev_b32_e32 v7, 16, v7
	v_pk_fma_f32 v[30:31], v[18:19], v[32:33], v[30:31] op_sel:[0,0,1] op_sel_hi:[1,0,0]
	v_pk_fma_f32 v[2:3], v[12:13], v[8:9], v[2:3]
	v_pk_fma_f32 v[30:31], v[10:11], v[6:7], v[30:31]
	v_pk_add_f32 v[2:3], v[16:17], v[2:3]
	v_pk_add_f32 v[30:31], v[14:15], v[30:31]
	v_mov_b32_e32 v42, v41
	v_pk_mul_f32 v[2:3], v[2:3], v[30:31]
	v_pk_mov_b32 v[30:31], v[8:9], v[48:49] op_sel:[1,0]
	v_cvt_pk_bf16_f32 v2, v2, v3
	v_pk_mul_f32 v[30:31], v[28:29], v[30:31]
	v_mov_b32_e32 v46, v45
	v_pk_fma_f32 v[8:9], v[24:25], v[8:9], v[30:31]
	v_pk_mov_b32 v[30:31], v[6:7], v[4:5] op_sel:[1,0]
	v_pk_fma_f32 v[8:9], v[12:13], v[48:49], v[8:9]
	v_pk_mul_f32 v[30:31], v[26:27], v[30:31]
	v_pk_add_f32 v[8:9], v[16:17], v[8:9]
	v_pk_fma_f32 v[6:7], v[22:23], v[6:7], v[30:31]
	v_mov_b32_e32 v34, v43
	v_pk_fma_f32 v[6:7], v[10:11], v[4:5], v[6:7]
	v_mov_b32_e32 v32, v47
	v_pk_add_f32 v[6:7], v[14:15], v[6:7]
	v_lshlrev_b32_e32 v173, 1, v170
	v_pk_mul_f32 v[6:7], v[8:9], v[6:7]
	v_pk_mov_b32 v[8:9], v[4:5], v[44:45] op_sel:[1,0]
	v_cvt_pk_bf16_f32 v3, v6, v7
	v_pk_mov_b32 v[6:7], v[48:49], v[40:41] op_sel:[1,0]
	v_pk_mul_f32 v[8:9], v[26:27], v[8:9]
	v_pk_mul_f32 v[6:7], v[28:29], v[6:7]
	v_pk_fma_f32 v[4:5], v[22:23], v[4:5], v[8:9]
	v_pk_fma_f32 v[6:7], v[24:25], v[48:49], v[6:7]
	v_pk_fma_f32 v[4:5], v[10:11], v[44:45], v[4:5]
	v_pk_fma_f32 v[6:7], v[12:13], v[40:41], v[6:7]
	v_pk_add_f32 v[4:5], v[14:15], v[4:5]
	v_pk_add_f32 v[6:7], v[16:17], v[6:7]
	v_pk_mul_f32 v[8:9], v[26:27], v[46:47]
	v_pk_mul_f32 v[4:5], v[6:7], v[4:5]
	v_pk_mul_f32 v[6:7], v[28:29], v[42:43]
	v_pk_fma_f32 v[8:9], v[22:23], v[44:45], v[8:9]
	v_pk_fma_f32 v[6:7], v[24:25], v[40:41], v[6:7]
	v_pk_fma_f32 v[8:9], v[10:11], v[32:33], v[8:9]
	v_pk_fma_f32 v[6:7], v[12:13], v[34:35], v[6:7]
	v_pk_add_f32 v[8:9], v[14:15], v[8:9]
	v_pk_add_f32 v[6:7], v[16:17], v[6:7]
	v_cvt_pk_bf16_f32 v4, v4, v5
	v_pk_mul_f32 v[6:7], v[6:7], v[8:9]
	v_add_u32_e32 v224, 0x400, v111
	v_cvt_pk_bf16_f32 v5, v6, v7
	v_add_u32_e32 v6, 0x400, v170
	v_ashrrev_i32_e32 v6, 1, v6
	v_mul_i32_i24_e32 v7, 0x3c00, v169
	v_and_b32_e32 v6, -16, v6
	v_add3_u32 v6, v7, v173, v6
	ds_write_b128 v6, v[2:5] offset:18560
	v_ashrrev_i32_e32 v2, 31, v224
	v_lshrrev_b32_e32 v225, 23, v2
	v_lshlrev_b32_e32 v128, 3, v224
	v_add_u32_e32 v2, v224, v225
	v_ashrrev_i32_e32 v129, 31, v128
	v_ashrrev_i32_e32 v171, 9, v2
	v_lshlrev_b64 v[140:141], 1, v[128:129]
	v_lshlrev_b32_e32 v2, 12, v171
	v_lshl_add_u64 v[32:33], s[28:29], 0, v[140:141]
	v_lshl_add_u64 v[30:31], s[38:39], 0, v[140:141]
	v_sub_u32_e32 v172, v128, v2
	global_load_dwordx4 v[2:5], v[32:33], off
	global_load_dwordx4 v[6:9], v[30:31], off
	v_cmp_lt_i32_e32 vcc, 0, v172
	v_mov_b32_e32 v35, 0
	v_mov_b32_e32 v37, 0
	s_and_saveexec_b64 s[0:1], vcc
	s_cbranch_execz .LBB0_589
	global_load_ushort v37, v[32:33], off offset:-2
.LBB0_589:
	s_or_b64 exec, exec, s[0:1]
	s_movk_i32 s0, 0xff8
	v_cmp_gt_i32_e64 s[0:1], s0, v172
	s_and_saveexec_b64 s[40:41], s[0:1]
	s_cbranch_execz .LBB0_591
	global_load_ushort v35, v[32:33], off offset:16

.LBB0_595:
	s_or_b64 exec, exec, s[40:41]
	s_waitcnt vmcnt(0)
	v_lshlrev_b32_e32 v37, 16, v37
	v_lshlrev_b32_e32 v35, 16, v35
	v_lshlrev_b32_e32 v39, 16, v39
	v_lshlrev_b32_e32 v33, 16, v33
	v_lshlrev_b32_e32 v41, 16, v5
	v_and_b32_e32 v43, 0xffff0000, v5
	s_waitcnt vmcnt(0)
	v_and_b32_e32 v44, 0xffff0000, v8
	v_lshlrev_b32_e32 v5, 16, v8
	v_and_b32_e32 v8, 0xffff0000, v2
	v_lshlrev_b32_e32 v32, 16, v6
	v_and_b32_e32 v6, 0xffff0000, v6
	v_mov_b32_e32 v36, v8
	v_lshlrev_b32_e32 v30, 16, v2
	v_lshlrev_b32_e32 v45, 16, v9
	v_and_b32_e32 v47, 0xffff0000, v9
	v_and_b32_e32 v48, 0xffff0000, v3
	v_lshlrev_b32_e32 v9, 16, v3
	v_pk_mul_f32 v[2:3], v[20:21], v[36:37]
	v_mov_b32_e32 v38, v6
	v_pk_fma_f32 v[2:3], v[20:21], v[30:31], v[2:3] op_sel:[0,0,1] op_sel_hi:[1,0,0]
	v_pk_mul_f32 v[30:31], v[18:19], v[38:39]
	v_and_b32_e32 v40, 0xffff0000, v4
	v_lshlrev_b32_e32 v49, 16, v4
	v_and_b32_e32 v4, 0xffff0000, v7
	v_lshlrev_b32_e32 v7, 16, v7
	v_pk_fma_f32 v[30:31], v[18:19], v[32:33], v[30:31] op_sel:[0,0,1] op_sel_hi:[1,0,0]
	v_pk_fma_f32 v[2:3], v[12:13], v[8:9], v[2:3]
	v_pk_fma_f32 v[30:31], v[10:11], v[6:7], v[30:31]
	v_pk_add_f32 v[2:3], v[16:17], v[2:3]
	v_pk_add_f32 v[30:31], v[14:15], v[30:31]
	v_mov_b32_e32 v42, v41
	v_pk_mul_f32 v[2:3], v[2:3], v[30:31]
	v_pk_mov_b32 v[30:31], v[8:9], v[48:49] op_sel:[1,0]
	v_cvt_pk_bf16_f32 v2, v2, v3
	v_pk_mul_f32 v[30:31], v[28:29], v[30:31]
	v_mov_b32_e32 v46, v45
	v_pk_fma_f32 v[8:9], v[24:25], v[8:9], v[30:31]
	v_pk_mov_b32 v[30:31], v[6:7], v[4:5] op_sel:[1,0]
	v_pk_fma_f32 v[8:9], v[12:13], v[48:49], v[8:9]
	v_pk_mul_f32 v[30:31], v[26:27], v[30:31]
	v_pk_add_f32 v[8:9], v[16:17], v[8:9]
	v_pk_fma_f32 v[6:7], v[22:23], v[6:7], v[30:31]
	v_mov_b32_e32 v34, v43
	v_pk_fma_f32 v[6:7], v[10:11], v[4:5], v[6:7]
	v_mov_b32_e32 v32, v47
	v_pk_add_f32 v[6:7], v[14:15], v[6:7]
	v_lshlrev_b32_e32 v176, 1, v172
	v_pk_mul_f32 v[6:7], v[8:9], v[6:7]
	v_pk_mov_b32 v[8:9], v[4:5], v[44:45] op_sel:[1,0]
	v_cvt_pk_bf16_f32 v3, v6, v7
	v_pk_mov_b32 v[6:7], v[48:49], v[40:41] op_sel:[1,0]
	v_pk_mul_f32 v[8:9], v[26:27], v[8:9]
	v_pk_mul_f32 v[6:7], v[28:29], v[6:7]
	v_pk_fma_f32 v[4:5], v[22:23], v[4:5], v[8:9]
	v_pk_fma_f32 v[6:7], v[24:25], v[48:49], v[6:7]
	v_pk_fma_f32 v[4:5], v[10:11], v[44:45], v[4:5]
	v_pk_fma_f32 v[6:7], v[12:13], v[40:41], v[6:7]
	v_pk_add_f32 v[4:5], v[14:15], v[4:5]
	v_pk_add_f32 v[6:7], v[16:17], v[6:7]
	v_pk_mul_f32 v[8:9], v[26:27], v[46:47]
	v_pk_mul_f32 v[4:5], v[6:7], v[4:5]
	v_pk_mul_f32 v[6:7], v[28:29], v[42:43]
	v_pk_fma_f32 v[8:9], v[22:23], v[44:45], v[8:9]
	v_pk_fma_f32 v[6:7], v[24:25], v[40:41], v[6:7]
	v_pk_fma_f32 v[8:9], v[10:11], v[32:33], v[8:9]
	v_pk_fma_f32 v[6:7], v[12:13], v[34:35], v[6:7]
	v_pk_add_f32 v[8:9], v[14:15], v[8:9]
	v_pk_add_f32 v[6:7], v[16:17], v[6:7]
	v_cvt_pk_bf16_f32 v4, v4, v5
	v_pk_mul_f32 v[6:7], v[6:7], v[8:9]
	v_add_u32_e32 v227, 0x500, v111
	v_cvt_pk_bf16_f32 v5, v6, v7
	v_add_u32_e32 v6, 0x400, v172
	v_ashrrev_i32_e32 v6, 1, v6
	v_mul_i32_i24_e32 v7, 0x3c00, v171
	v_and_b32_e32 v6, -16, v6
	v_add3_u32 v6, v7, v176, v6
	ds_write_b128 v6, v[2:5] offset:18560
	v_ashrrev_i32_e32 v2, 31, v227
	v_lshrrev_b32_e32 v228, 23, v2
	v_lshlrev_b32_e32 v130, 3, v227
	v_add_u32_e32 v2, v227, v228
	v_ashrrev_i32_e32 v131, 31, v130
	v_ashrrev_i32_e32 v177, 9, v2
	v_lshlrev_b64 v[142:143], 1, v[130:131]
	v_lshlrev_b32_e32 v2, 12, v177
	v_lshl_add_u64 v[32:33], s[28:29], 0, v[142:143]
	v_lshl_add_u64 v[30:31], s[38:39], 0, v[142:143]
	v_sub_u32_e32 v178, v130, v2
	global_load_dwordx4 v[2:5], v[32:33], off
	global_load_dwordx4 v[6:9], v[30:31], off
	v_cmp_lt_i32_e32 vcc, 0, v178
	v_mov_b32_e32 v35, 0
	v_mov_b32_e32 v37, 0
	s_and_saveexec_b64 s[0:1], vcc
	s_cbranch_execz .LBB0_597
	global_load_ushort v37, v[32:33], off offset:-2
.LBB0_597:
	s_or_b64 exec, exec, s[0:1]
	s_movk_i32 s0, 0xff8
	v_cmp_gt_i32_e64 s[0:1], s0, v178
	s_and_saveexec_b64 s[40:41], s[0:1]
	s_cbranch_execz .LBB0_599
	global_load_ushort v35, v[32:33], off offset:16

.LBB0_603:
	s_or_b64 exec, exec, s[40:41]
	s_waitcnt vmcnt(0)
	v_lshlrev_b32_e32 v37, 16, v37
	v_lshlrev_b32_e32 v35, 16, v35
	v_lshlrev_b32_e32 v39, 16, v39
	v_lshlrev_b32_e32 v33, 16, v33
	v_lshlrev_b32_e32 v41, 16, v5
	v_and_b32_e32 v43, 0xffff0000, v5
	s_waitcnt vmcnt(0)
	v_and_b32_e32 v44, 0xffff0000, v8
	v_lshlrev_b32_e32 v5, 16, v8
	v_and_b32_e32 v8, 0xffff0000, v2
	v_lshlrev_b32_e32 v32, 16, v6
	v_and_b32_e32 v6, 0xffff0000, v6
	v_mov_b32_e32 v36, v8
	v_lshlrev_b32_e32 v30, 16, v2
	v_lshlrev_b32_e32 v45, 16, v9
	v_and_b32_e32 v47, 0xffff0000, v9
	v_and_b32_e32 v48, 0xffff0000, v3
	v_lshlrev_b32_e32 v9, 16, v3
	v_pk_mul_f32 v[2:3], v[20:21], v[36:37]
	v_mov_b32_e32 v38, v6
	v_pk_fma_f32 v[2:3], v[20:21], v[30:31], v[2:3] op_sel:[0,0,1] op_sel_hi:[1,0,0]
	v_pk_mul_f32 v[30:31], v[18:19], v[38:39]
	v_and_b32_e32 v40, 0xffff0000, v4
	v_lshlrev_b32_e32 v49, 16, v4
	v_and_b32_e32 v4, 0xffff0000, v7
	v_lshlrev_b32_e32 v7, 16, v7
	v_pk_fma_f32 v[30:31], v[18:19], v[32:33], v[30:31] op_sel:[0,0,1] op_sel_hi:[1,0,0]
	v_pk_fma_f32 v[2:3], v[12:13], v[8:9], v[2:3]
	v_pk_fma_f32 v[30:31], v[10:11], v[6:7], v[30:31]
	v_pk_add_f32 v[2:3], v[16:17], v[2:3]
	v_pk_add_f32 v[30:31], v[14:15], v[30:31]
	v_mov_b32_e32 v42, v41
	v_pk_mul_f32 v[2:3], v[2:3], v[30:31]
	v_pk_mov_b32 v[30:31], v[8:9], v[48:49] op_sel:[1,0]
	v_cvt_pk_bf16_f32 v2, v2, v3
	v_pk_mul_f32 v[30:31], v[28:29], v[30:31]
	v_mov_b32_e32 v46, v45
	v_pk_fma_f32 v[8:9], v[24:25], v[8:9], v[30:31]
	v_pk_mov_b32 v[30:31], v[6:7], v[4:5] op_sel:[1,0]
	v_pk_fma_f32 v[8:9], v[12:13], v[48:49], v[8:9]
	v_pk_mul_f32 v[30:31], v[26:27], v[30:31]
	v_pk_add_f32 v[8:9], v[16:17], v[8:9]
	v_pk_fma_f32 v[6:7], v[22:23], v[6:7], v[30:31]
	v_mov_b32_e32 v34, v43
	v_pk_fma_f32 v[6:7], v[10:11], v[4:5], v[6:7]
	v_mov_b32_e32 v32, v47
	v_pk_add_f32 v[6:7], v[14:15], v[6:7]
	v_lshlrev_b32_e32 v218, 1, v178
	v_pk_mul_f32 v[6:7], v[8:9], v[6:7]
	v_pk_mov_b32 v[8:9], v[4:5], v[44:45] op_sel:[1,0]
	v_cvt_pk_bf16_f32 v3, v6, v7
	v_pk_mov_b32 v[6:7], v[48:49], v[40:41] op_sel:[1,0]
	v_pk_mul_f32 v[8:9], v[26:27], v[8:9]
	v_pk_mul_f32 v[6:7], v[28:29], v[6:7]
	v_pk_fma_f32 v[4:5], v[22:23], v[4:5], v[8:9]
	v_pk_fma_f32 v[6:7], v[24:25], v[48:49], v[6:7]
	v_pk_fma_f32 v[4:5], v[10:11], v[44:45], v[4:5]
	v_pk_fma_f32 v[6:7], v[12:13], v[40:41], v[6:7]
	v_pk_add_f32 v[4:5], v[14:15], v[4:5]
	v_pk_add_f32 v[6:7], v[16:17], v[6:7]
	v_pk_mul_f32 v[8:9], v[26:27], v[46:47]
	v_pk_mul_f32 v[4:5], v[6:7], v[4:5]
	v_pk_mul_f32 v[6:7], v[28:29], v[42:43]
	v_pk_fma_f32 v[8:9], v[22:23], v[44:45], v[8:9]
	v_pk_fma_f32 v[6:7], v[24:25], v[40:41], v[6:7]
	v_pk_fma_f32 v[8:9], v[10:11], v[32:33], v[8:9]
	v_pk_fma_f32 v[6:7], v[12:13], v[34:35], v[6:7]
	v_pk_add_f32 v[8:9], v[14:15], v[8:9]
	v_pk_add_f32 v[6:7], v[16:17], v[6:7]
	v_cvt_pk_bf16_f32 v4, v4, v5
	v_pk_mul_f32 v[6:7], v[6:7], v[8:9]
	v_add_u32_e32 v229, 0x600, v111
	v_cvt_pk_bf16_f32 v5, v6, v7
	v_add_u32_e32 v6, 0x400, v178
	v_ashrrev_i32_e32 v6, 1, v6
	v_mul_i32_i24_e32 v7, 0x3c00, v177
	v_and_b32_e32 v6, -16, v6
	v_add3_u32 v6, v7, v218, v6
	ds_write_b128 v6, v[2:5] offset:18560
	v_ashrrev_i32_e32 v2, 31, v229
	v_lshrrev_b32_e32 v230, 23, v2
	v_lshlrev_b32_e32 v134, 3, v229
	v_add_u32_e32 v2, v229, v230
	v_ashrrev_i32_e32 v135, 31, v134
	v_ashrrev_i32_e32 v180, 9, v2
	v_lshlrev_b64 v[144:145], 1, v[134:135]
	v_lshlrev_b32_e32 v2, 12, v180
	v_lshl_add_u64 v[32:33], s[28:29], 0, v[144:145]
	v_lshl_add_u64 v[30:31], s[38:39], 0, v[144:145]
	v_sub_u32_e32 v181, v134, v2
	global_load_dwordx4 v[2:5], v[32:33], off
	global_load_dwordx4 v[6:9], v[30:31], off
	v_cmp_lt_i32_e32 vcc, 0, v181
	v_mov_b32_e32 v35, 0
	v_mov_b32_e32 v37, 0
	s_and_saveexec_b64 s[0:1], vcc
	s_cbranch_execz .LBB0_605
	global_load_ushort v37, v[32:33], off offset:-2
.LBB0_605:
	s_or_b64 exec, exec, s[0:1]
	s_movk_i32 s0, 0xff8
	v_cmp_gt_i32_e64 s[0:1], s0, v181
	s_and_saveexec_b64 s[40:41], s[0:1]
	s_cbranch_execz .LBB0_607
	global_load_ushort v35, v[32:33], off offset:16

.LBB0_611:
	s_or_b64 exec, exec, s[40:41]
	s_waitcnt vmcnt(0)
	v_lshlrev_b32_e32 v37, 16, v37
	v_lshlrev_b32_e32 v35, 16, v35
	v_lshlrev_b32_e32 v39, 16, v39
	v_lshlrev_b32_e32 v33, 16, v33
	v_lshlrev_b32_e32 v41, 16, v5
	v_and_b32_e32 v43, 0xffff0000, v5
	s_waitcnt vmcnt(0)
	v_and_b32_e32 v44, 0xffff0000, v8
	v_lshlrev_b32_e32 v5, 16, v8
	v_and_b32_e32 v8, 0xffff0000, v2
	v_lshlrev_b32_e32 v32, 16, v6
	v_and_b32_e32 v6, 0xffff0000, v6
	v_mov_b32_e32 v36, v8
	v_lshlrev_b32_e32 v30, 16, v2
	v_lshlrev_b32_e32 v45, 16, v9
	v_and_b32_e32 v47, 0xffff0000, v9
	v_and_b32_e32 v48, 0xffff0000, v3
	v_lshlrev_b32_e32 v9, 16, v3
	v_pk_mul_f32 v[2:3], v[20:21], v[36:37]
	v_mov_b32_e32 v38, v6
	v_pk_fma_f32 v[2:3], v[20:21], v[30:31], v[2:3] op_sel:[0,0,1] op_sel_hi:[1,0,0]
	v_pk_mul_f32 v[30:31], v[18:19], v[38:39]
	v_and_b32_e32 v40, 0xffff0000, v4
	v_lshlrev_b32_e32 v49, 16, v4
	v_and_b32_e32 v4, 0xffff0000, v7
	v_lshlrev_b32_e32 v7, 16, v7
	v_pk_fma_f32 v[30:31], v[18:19], v[32:33], v[30:31] op_sel:[0,0,1] op_sel_hi:[1,0,0]
	v_pk_fma_f32 v[2:3], v[12:13], v[8:9], v[2:3]
	v_pk_fma_f32 v[30:31], v[10:11], v[6:7], v[30:31]
	v_pk_add_f32 v[2:3], v[16:17], v[2:3]
	v_pk_add_f32 v[30:31], v[14:15], v[30:31]
	v_mov_b32_e32 v42, v41
	v_pk_mul_f32 v[2:3], v[2:3], v[30:31]
	v_pk_mov_b32 v[30:31], v[8:9], v[48:49] op_sel:[1,0]
	v_cvt_pk_bf16_f32 v2, v2, v3
	v_pk_mul_f32 v[30:31], v[28:29], v[30:31]
	v_mov_b32_e32 v46, v45
	v_pk_fma_f32 v[8:9], v[24:25], v[8:9], v[30:31]
	v_pk_mov_b32 v[30:31], v[6:7], v[4:5] op_sel:[1,0]
	v_pk_fma_f32 v[8:9], v[12:13], v[48:49], v[8:9]
	v_pk_mul_f32 v[30:31], v[26:27], v[30:31]
	v_pk_add_f32 v[8:9], v[16:17], v[8:9]
	v_pk_fma_f32 v[6:7], v[22:23], v[6:7], v[30:31]
	v_mov_b32_e32 v34, v43
	v_pk_fma_f32 v[6:7], v[10:11], v[4:5], v[6:7]
	v_mov_b32_e32 v32, v47
	v_pk_add_f32 v[6:7], v[14:15], v[6:7]
	v_lshlrev_b32_e32 v221, 1, v181
	v_pk_mul_f32 v[6:7], v[8:9], v[6:7]
	v_pk_mov_b32 v[8:9], v[4:5], v[44:45] op_sel:[1,0]
	v_cvt_pk_bf16_f32 v3, v6, v7
	v_pk_mov_b32 v[6:7], v[48:49], v[40:41] op_sel:[1,0]
	v_pk_mul_f32 v[8:9], v[26:27], v[8:9]
	v_pk_mul_f32 v[6:7], v[28:29], v[6:7]
	v_pk_fma_f32 v[4:5], v[22:23], v[4:5], v[8:9]
	v_pk_fma_f32 v[6:7], v[24:25], v[48:49], v[6:7]
	v_pk_fma_f32 v[4:5], v[10:11], v[44:45], v[4:5]
	v_pk_fma_f32 v[6:7], v[12:13], v[40:41], v[6:7]
	v_pk_add_f32 v[4:5], v[14:15], v[4:5]
	v_pk_add_f32 v[6:7], v[16:17], v[6:7]
	v_pk_mul_f32 v[8:9], v[26:27], v[46:47]
	v_pk_mul_f32 v[4:5], v[6:7], v[4:5]
	v_pk_mul_f32 v[6:7], v[28:29], v[42:43]
	v_pk_fma_f32 v[8:9], v[22:23], v[44:45], v[8:9]
	v_pk_fma_f32 v[6:7], v[24:25], v[40:41], v[6:7]
	v_pk_fma_f32 v[8:9], v[10:11], v[32:33], v[8:9]
	v_pk_fma_f32 v[6:7], v[12:13], v[34:35], v[6:7]
	v_pk_add_f32 v[8:9], v[14:15], v[8:9]
	v_pk_add_f32 v[6:7], v[16:17], v[6:7]
	v_cvt_pk_bf16_f32 v4, v4, v5
	v_pk_mul_f32 v[6:7], v[6:7], v[8:9]
	v_add_u32_e32 v231, 0x700, v111
	v_cvt_pk_bf16_f32 v5, v6, v7
	v_add_u32_e32 v6, 0x400, v181
	v_ashrrev_i32_e32 v6, 1, v6
	v_mul_i32_i24_e32 v7, 0x3c00, v180
	v_and_b32_e32 v6, -16, v6
	v_add3_u32 v6, v7, v221, v6
	ds_write_b128 v6, v[2:5] offset:18560
	v_ashrrev_i32_e32 v2, 31, v231
	v_lshrrev_b32_e32 v232, 23, v2
	v_lshlrev_b32_e32 v136, 3, v231
	v_add_u32_e32 v2, v231, v232
	v_ashrrev_i32_e32 v137, 31, v136
	v_ashrrev_i32_e32 v222, 9, v2
	v_lshlrev_b64 v[156:157], 1, v[136:137]
	v_lshlrev_b32_e32 v2, 12, v222
	v_lshl_add_u64 v[32:33], s[28:29], 0, v[156:157]
	v_lshl_add_u64 v[30:31], s[38:39], 0, v[156:157]
	v_sub_u32_e32 v223, v136, v2
	global_load_dwordx4 v[2:5], v[32:33], off
	global_load_dwordx4 v[6:9], v[30:31], off
	v_cmp_lt_i32_e32 vcc, 0, v223
	v_mov_b32_e32 v35, 0
	v_mov_b32_e32 v37, 0
	s_and_saveexec_b64 s[0:1], vcc
	s_cbranch_execz .LBB0_613
	global_load_ushort v37, v[32:33], off offset:-2
.LBB0_613:
	s_or_b64 exec, exec, s[0:1]
	s_movk_i32 s0, 0xff8
	v_cmp_gt_i32_e64 s[0:1], s0, v223
	s_and_saveexec_b64 s[28:29], s[0:1]
	s_cbranch_execz .LBB0_615
	global_load_ushort v35, v[32:33], off offset:16
.LBB0_615:
	s_or_b64 exec, exec, s[28:29]
	v_mov_b32_e32 v33, 0
	v_mov_b32_e32 v39, 0
	s_and_saveexec_b64 s[28:29], vcc
	s_cbranch_execz .LBB0_617
	global_load_ushort v39, v[30:31], off offset:-2

.LBB0_619:
	s_or_b64 exec, exec, s[28:29]
	s_waitcnt vmcnt(0)
	v_lshlrev_b32_e32 v37, 16, v37
	v_lshlrev_b32_e32 v35, 16, v35
	v_lshlrev_b32_e32 v39, 16, v39
	v_lshlrev_b32_e32 v33, 16, v33
	v_lshlrev_b32_e32 v41, 16, v5
	v_and_b32_e32 v43, 0xffff0000, v5
	s_waitcnt vmcnt(0)
	v_and_b32_e32 v44, 0xffff0000, v8
	v_lshlrev_b32_e32 v5, 16, v8
	v_and_b32_e32 v8, 0xffff0000, v2
	v_lshlrev_b32_e32 v30, 16, v6
	v_and_b32_e32 v6, 0xffff0000, v6
	v_mov_b32_e32 v36, v8
	v_lshrrev_b32_e32 v233, 5, v0
	v_lshlrev_b32_e32 v0, 16, v2
	v_lshlrev_b32_e32 v45, 16, v9
	v_and_b32_e32 v47, 0xffff0000, v9
	v_and_b32_e32 v48, 0xffff0000, v3
	v_lshlrev_b32_e32 v9, 16, v3
	v_pk_mul_f32 v[2:3], v[20:21], v[36:37]
	v_mov_b32_e32 v38, v6
	v_and_b32_e32 v31, 31, v111
	v_pk_fma_f32 v[2:3], v[20:21], v[0:1], v[2:3] op_sel:[0,0,1] op_sel_hi:[1,0,0]
	v_pk_mul_f32 v[20:21], v[18:19], v[38:39]
	v_and_b32_e32 v40, 0xffff0000, v4
	v_lshlrev_b32_e32 v49, 16, v4
	v_and_b32_e32 v4, 0xffff0000, v7
	v_lshlrev_b32_e32 v7, 16, v7
	v_pk_fma_f32 v[18:19], v[18:19], v[30:31], v[20:21] op_sel:[0,0,1] op_sel_hi:[1,0,0]
	v_pk_fma_f32 v[2:3], v[12:13], v[8:9], v[2:3]
	v_pk_fma_f32 v[18:19], v[10:11], v[6:7], v[18:19]
	v_pk_add_f32 v[2:3], v[16:17], v[2:3]
	v_pk_add_f32 v[18:19], v[14:15], v[18:19]
	v_mov_b32_e32 v42, v41
	v_pk_mul_f32 v[2:3], v[2:3], v[18:19]
	v_pk_mov_b32 v[18:19], v[8:9], v[48:49] op_sel:[1,0]
	v_cvt_pk_bf16_f32 v2, v2, v3
	v_pk_mul_f32 v[18:19], v[28:29], v[18:19]
	v_mov_b32_e32 v46, v45
	v_pk_fma_f32 v[8:9], v[24:25], v[8:9], v[18:19]
	v_pk_mov_b32 v[18:19], v[6:7], v[4:5] op_sel:[1,0]
	v_pk_fma_f32 v[8:9], v[12:13], v[48:49], v[8:9]
	v_pk_mul_f32 v[18:19], v[26:27], v[18:19]
	v_pk_add_f32 v[8:9], v[16:17], v[8:9]
	v_pk_fma_f32 v[6:7], v[22:23], v[6:7], v[18:19]
	v_mov_b32_e32 v34, v43
	v_pk_fma_f32 v[6:7], v[10:11], v[4:5], v[6:7]
	v_mov_b32_e32 v32, v47
	v_pk_add_f32 v[6:7], v[14:15], v[6:7]
	v_add_u32_e32 v0, 0x400, v223
	v_pk_mul_f32 v[6:7], v[8:9], v[6:7]
	v_pk_mov_b32 v[8:9], v[4:5], v[44:45] op_sel:[1,0]
	v_cvt_pk_bf16_f32 v3, v6, v7
	v_pk_mov_b32 v[6:7], v[48:49], v[40:41] op_sel:[1,0]
	v_pk_mul_f32 v[8:9], v[26:27], v[8:9]
	v_pk_mul_f32 v[6:7], v[28:29], v[6:7]
	v_pk_fma_f32 v[4:5], v[22:23], v[4:5], v[8:9]
	v_pk_fma_f32 v[6:7], v[24:25], v[48:49], v[6:7]
	v_pk_fma_f32 v[4:5], v[10:11], v[44:45], v[4:5]
	v_pk_fma_f32 v[6:7], v[12:13], v[40:41], v[6:7]
	v_pk_add_f32 v[4:5], v[14:15], v[4:5]
	v_pk_add_f32 v[6:7], v[16:17], v[6:7]
	v_pk_mul_f32 v[8:9], v[26:27], v[46:47]
	v_pk_mul_f32 v[4:5], v[6:7], v[4:5]
	v_pk_mul_f32 v[6:7], v[28:29], v[42:43]
	v_pk_fma_f32 v[8:9], v[22:23], v[44:45], v[8:9]
	v_pk_fma_f32 v[6:7], v[24:25], v[40:41], v[6:7]
	v_pk_fma_f32 v[8:9], v[10:11], v[32:33], v[8:9]
	v_pk_fma_f32 v[6:7], v[12:13], v[34:35], v[6:7]
	v_pk_add_f32 v[8:9], v[14:15], v[8:9]
	v_pk_add_f32 v[6:7], v[16:17], v[6:7]
	v_ashrrev_i32_e32 v0, 1, v0
	v_pk_mul_f32 v[6:7], v[6:7], v[8:9]
	v_cvt_pk_bf16_f32 v4, v4, v5
	v_cvt_pk_bf16_f32 v5, v6, v7
	v_mul_i32_i24_e32 v6, 0x3c00, v222
	v_lshlrev_b32_e32 v226, 1, v223
	v_and_b32_e32 v0, -16, v0
	v_add3_u32 v0, v6, v226, v0
	ds_write_b128 v0, v[2:5] offset:18560
	v_lshlrev_b32_e32 v235, 1, v31
	v_lshlrev_b32_e32 v5, 4, v233
	v_xad_u32 v2, v5, 16, v235
	s_waitcnt lgkmcnt(0)
	s_barrier
	v_lshlrev_b32_e32 v0, 3, v233
	ds_read_b32 v6, v2 offset:14
	v_or_b32_e32 v2, 7, v0
	v_lshlrev_b32_e32 v234, 5, v31
	v_sub_u32_e32 v2, v31, v2
	v_or_b32_e32 v0, v234, v0
	v_lshlrev_b32_e32 v2, 1, v2
	s_movk_i32 s0, 0x1e00
	v_add_u16_e32 v8, 0x13f0, v0
	ds_read_b96 v[2:4], v2 offset:32
	ds_read_b128 v[66:69], v1 offset:16512
	v_mul_lo_u32 v236, v159, s0
	v_lshrrev_b16_e32 v8, 1, v8
	s_waitcnt lgkmcnt(2)
	v_alignbit_b32 v94, v6, v6, 16
	v_lshlrev_b32_e32 v6, 1, v0
	v_lshlrev_b32_e32 v7, 1, v236
	v_and_b32_e32 v8, 0x7ff0, v8
	v_add3_u32 v6, v6, v7, v8
	ds_read_b128 v[70:73], v6 offset:26720
	s_waitcnt lgkmcnt(2)
	v_alignbit_b32 v97, v2, v2, 16
	v_sub_u32_e32 v2, v235, v5
	v_mov_b32_e32 v14, v1
	v_mov_b32_e32 v15, v1
	v_alignbit_b32 v95, v4, v4, 16
	v_alignbit_b32 v96, v3, v3, 16
	v_add_u32_e32 v237, 50, v2
	v_add_u32_e32 v238, 0x13d0, v0
	v_mov_b32_e32 v0, v1
	v_mov_b32_e32 v2, v1
	v_mov_b32_e32 v3, v1
	v_mov_b32_e32 v4, v1
	v_mov_b32_e32 v5, v1
	v_mov_b32_e32 v6, v1
	v_mov_b32_e32 v7, v1
	v_mov_b32_e32 v8, v1
	v_mov_b32_e32 v9, v1
	v_mov_b32_e32 v10, v1
	v_mov_b32_e32 v11, v1
	v_mov_b32_e32 v12, v1
	v_mov_b32_e32 v13, v1
	v_mov_b64_e32 v[64:65], v[14:15]
	v_mov_b64_e32 v[48:49], v[14:15]
	v_mov_b64_e32 v[32:33], v[14:15]
	s_waitcnt lgkmcnt(1)
	v_mov_b64_e32 v[80:81], v[68:69]
	v_mov_b64_e32 v[76:77], v[68:69]
	v_mov_b64_e32 v[62:63], v[12:13]
	v_mov_b64_e32 v[60:61], v[10:11]
	v_mov_b64_e32 v[58:59], v[8:9]
	v_mov_b64_e32 v[56:57], v[6:7]
	v_mov_b64_e32 v[54:55], v[4:5]
	v_mov_b64_e32 v[52:53], v[2:3]
	v_mov_b64_e32 v[50:51], v[0:1]
	v_mov_b64_e32 v[46:47], v[12:13]
	v_mov_b64_e32 v[44:45], v[10:11]
	v_mov_b64_e32 v[42:43], v[8:9]
	v_mov_b64_e32 v[40:41], v[6:7]
	v_mov_b64_e32 v[38:39], v[4:5]
	v_mov_b64_e32 v[36:37], v[2:3]
	v_mov_b64_e32 v[34:35], v[0:1]
	v_mov_b64_e32 v[30:31], v[12:13]
	v_mov_b64_e32 v[28:29], v[10:11]
	v_mov_b64_e32 v[26:27], v[8:9]
	v_mov_b64_e32 v[24:25], v[6:7]
	v_mov_b64_e32 v[22:23], v[4:5]
	v_mov_b64_e32 v[20:21], v[2:3]
	v_mov_b64_e32 v[18:19], v[0:1]
	v_mov_b64_e32 v[16:17], v[14:15]
	s_movk_i32 s5, 0xfeff
	v_mov_b64_e32 v[78:79], v[66:67]
	v_mov_b64_e32 v[74:75], v[66:67]
	v_mov_b64_e32 v[14:15], v[12:13]
	v_mov_b64_e32 v[12:13], v[10:11]
	v_mov_b64_e32 v[10:11], v[8:9]
	v_mov_b64_e32 v[8:9], v[6:7]
	v_mov_b64_e32 v[6:7], v[4:5]
	v_mov_b64_e32 v[4:5], v[2:3]
	v_mov_b64_e32 v[2:3], v[0:1]
	s_waitcnt lgkmcnt(0)
	v_and_b32_e32 v248, 31, v151
	v_bfe_u32 v245, v151, 5, 1
	v_lshrrev_b32_e32 v247, 6, v151
	v_lshlrev_b32_e32 v244, 3, v245
	v_sub_u32_e32 v244, v248, v244
	v_add_u32_e32 v244, 9, v244
	v_and_b32_e32 v249, 1, v244
	v_cmp_eq_u32_e32 vcc, 1, v249
	v_lshrrev_b32_e32 v244, 1, v244
	v_lshlrev_b32_e32 v244, 2, v244
	s_mov_b32 s5, 0xffff
	v_mul_u32_u24_e32 v246, 80, v248
	v_lshl_add_u32 v246, v245, 4, v246
	v_mul_u32_u24_e32 v247, 0x3c00, v247
	v_add_u32_e32 v247, v246, v247
	v_add_u32_e32 v247, 0x7230, v247
	v_add_u32_e32 v246, 32, v247
	v_add_u32_e32 v245, 32, v244
	ds_read2_b32 v[66:67], v244 offset1:1
	ds_read2_b32 v[68:69], v244 offset0:2 offset1:3
	ds_read_b32 v70, v244 offset:16
	v_add_u32_e32 v244, 64, v244
	ds_read_b128 v[76:79], v246 offset:0
	v_add_u32_e32 v246, 0xffffffb0, v246
	ds_read2_b32 v[92:93], v245 offset1:1
	ds_read2_b32 v[94:95], v245 offset0:2 offset1:3
	ds_read_b32 v96, v245 offset:16
	v_add_u32_e32 v245, 64, v245
	s_waitcnt lgkmcnt(3)
	v_alignbit_b32 v72, v69, v69, 16
	v_bfi_b32 v249, s5, v70, v69
	v_cndmask_b32_e32 v72, v72, v249, vcc
	v_alignbit_b32 v73, v68, v68, 16
	v_bfi_b32 v249, s5, v69, v68
	v_cndmask_b32_e32 v73, v73, v249, vcc
	v_alignbit_b32 v74, v67, v67, 16
	v_bfi_b32 v249, s5, v68, v67
	v_cndmask_b32_e32 v74, v74, v249, vcc
	v_alignbit_b32 v75, v66, v66, 16
	v_bfi_b32 v249, s5, v67, v66
	v_cndmask_b32_e32 v75, v75, v249, vcc
	s_mov_b32 s4, 31

.LBB0_638:
	v_lshlrev_b32_e32 v0, 1, v234
	v_lshl_or_b32 v0, v233, 3, v0
	s_movk_i32 s0, 0x2200
	s_waitcnt lgkmcnt(2)
	v_mad_u64_u32 v[66:67], s[0:1], v159, s0, v[0:1]
	v_lshl_add_u32 v0, v235, 1, v66
	v_add_u32_e32 v67, 0x4080, v0
	v_cvt_pk_bf16_f32 v52, v52, v53
	v_cvt_pk_bf16_f32 v50, v50, v51
	s_waitcnt lgkmcnt(0)
	s_barrier
	ds_write2_b32 v67, v50, v52 offset1:1
	v_add_u32_e32 v50, 0x4090, v0
	v_cvt_pk_bf16_f32 v51, v56, v57
	v_cvt_pk_bf16_f32 v52, v54, v55
	ds_write2_b32 v50, v52, v51 offset1:1
	v_add_u32_e32 v50, 0x40a0, v0
	v_cvt_pk_bf16_f32 v51, v60, v61
	v_cvt_pk_bf16_f32 v52, v58, v59
	ds_write2_b32 v50, v52, v51 offset1:1
	v_add_u32_e32 v0, 0x40b0, v0
	v_cvt_pk_bf16_f32 v50, v64, v65
	v_cvt_pk_bf16_f32 v51, v62, v63
	ds_write2_b32 v0, v51, v50 offset1:1
	v_or_b32_e32 v0, 0x400, v234
	v_lshrrev_b32_e32 v0, 3, v0
	v_and_b32_e32 v0, 0xfc, v0
	v_add_u32_e32 v0, v66, v0
	v_add_u32_e32 v50, 0x4880, v0
	v_cvt_pk_bf16_f32 v36, v36, v37
	v_cvt_pk_bf16_f32 v34, v34, v35
	ds_write2_b32 v50, v34, v36 offset1:1
	v_add_u32_e32 v34, 0x4890, v0
	v_cvt_pk_bf16_f32 v35, v40, v41
	v_cvt_pk_bf16_f32 v36, v38, v39
	ds_write2_b32 v34, v36, v35 offset1:1
	v_add_u32_e32 v34, 0x48a0, v0
	v_cvt_pk_bf16_f32 v35, v44, v45
	v_cvt_pk_bf16_f32 v36, v42, v43
	ds_write2_b32 v34, v36, v35 offset1:1
	v_add_u32_e32 v0, 0x48b0, v0
	v_cvt_pk_bf16_f32 v34, v48, v49
	v_cvt_pk_bf16_f32 v35, v46, v47
	ds_write2_b32 v0, v35, v34 offset1:1
	v_or_b32_e32 v0, 0x800, v234
	v_lshrrev_b32_e32 v0, 3, v0
	v_and_b32_e32 v0, 0x17c, v0
	v_add_u32_e32 v0, v66, v0
	v_add_u32_e32 v34, 0x5080, v0
	v_cvt_pk_bf16_f32 v20, v20, v21
	v_cvt_pk_bf16_f32 v18, v18, v19
	ds_write2_b32 v34, v18, v20 offset1:1
	v_add_u32_e32 v18, 0x5090, v0
	v_cvt_pk_bf16_f32 v19, v24, v25
	v_cvt_pk_bf16_f32 v20, v22, v23
	ds_write2_b32 v18, v20, v19 offset1:1
	v_add_u32_e32 v18, 0x50a0, v0
	v_cvt_pk_bf16_f32 v19, v28, v29
	v_cvt_pk_bf16_f32 v20, v26, v27
	ds_write2_b32 v18, v20, v19 offset1:1
	v_add_u32_e32 v0, 0x50b0, v0
	v_cvt_pk_bf16_f32 v18, v32, v33
	v_cvt_pk_bf16_f32 v19, v30, v31
	ds_write2_b32 v0, v19, v18 offset1:1
	v_or_b32_e32 v0, 0xc00, v234
	s_mul_i32 s4, s50, 0xc000
	v_readlane_b32 s0, v253, 40
	v_lshrrev_b32_e32 v0, 3, v0
	s_mul_hi_u32 s5, s50, 0xc000
	s_add_u32 s0, s0, s4
	v_readlane_b32 s1, v253, 41
	v_and_b32_e32 v0, 0x1fc, v0
	s_addc_u32 s1, s1, s5
	v_add_u32_e32 v0, v66, v0
	s_add_u32 s0, s0, 0x4000
	v_add_u32_e32 v18, 0x5880, v0
	v_cvt_pk_bf16_f32 v4, v4, v5
	v_cvt_pk_bf16_f32 v2, v2, v3
	s_addc_u32 s1, s1, 0
	ds_write2_b32 v18, v2, v4 offset1:1
	v_add_u32_e32 v2, 0x5890, v0
	v_cvt_pk_bf16_f32 v3, v8, v9
	v_cvt_pk_bf16_f32 v4, v6, v7
	s_add_u32 s4, s94, s4
	ds_write2_b32 v2, v4, v3 offset1:1
	v_add_u32_e32 v2, 0x58a0, v0
	v_cvt_pk_bf16_f32 v3, v12, v13
	v_cvt_pk_bf16_f32 v4, v10, v11
	s_addc_u32 s5, s95, s5
	ds_write2_b32 v2, v4, v3 offset1:1
	v_add_u32_e32 v0, 0x58b0, v0
	v_cvt_pk_bf16_f32 v2, v16, v17
	v_cvt_pk_bf16_f32 v3, v14, v15
	s_add_u32 s28, s4, 0xb404000
	ds_write2_b32 v0, v3, v2 offset1:1
	s_addc_u32 s29, s5, 0
	v_lshl_add_u64 v[2:3], s[0:1], 0, v[122:123]
	s_waitcnt lgkmcnt(0)
	s_barrier
	v_lshl_add_u64 v[4:5], s[28:29], 0, v[122:123]
	global_load_dwordx4 v[62:65], v[2:3], off
	global_load_dwordx4 v[58:61], v[4:5], off
	v_add_lshl_u32 v0, v111, v164, 3
	v_and_b32_e32 v0, 0xfffff000, v0
	v_sub_u32_e32 v0, v118, v0
	v_cmp_lt_i32_e32 vcc, 0, v0
	v_mov_b32_e32 v95, 0
	v_mov_b32_e32 v97, 0
	s_and_saveexec_b64 s[38:39], vcc
	s_cbranch_execz .LBB0_640
	global_load_ushort v97, v[2:3], off offset:-2
.LBB0_640:
	s_or_b64 exec, exec, s[38:39]
	s_movk_i32 s6, 0xff8
	v_cmp_gt_i32_e32 vcc, s6, v0
	s_and_saveexec_b64 s[38:39], vcc
	s_movk_i32 s50, 0x3000
	s_cbranch_execz .LBB0_642
	global_load_ushort v95, v[2:3], off offset:16
.LBB0_642:
	s_or_b64 exec, exec, s[38:39]
	v_lshl_add_u64 v[2:3], s[0:1], 0, v[126:127]
	v_lshl_add_u64 v[4:5], s[28:29], 0, v[126:127]
	global_load_dwordx4 v[54:57], v[2:3], off
	global_load_dwordx4 v[46:49], v[4:5], off
	v_add_lshl_u32 v0, v115, v166, 3
	v_and_b32_e32 v0, 0xfffff000, v0
	v_sub_u32_e32 v0, v116, v0
	v_cmp_lt_i32_e32 vcc, 0, v0
	v_mov_b32_e32 v89, 0
	v_mov_b32_e32 v93, 0
	s_and_saveexec_b64 s[38:39], vcc
	s_cbranch_execz .LBB0_644
	global_load_ushort v93, v[2:3], off offset:-2
.LBB0_644:
	s_or_b64 exec, exec, s[38:39]
	v_cmp_gt_i32_e32 vcc, s6, v0
	s_and_saveexec_b64 s[38:39], vcc
	s_cbranch_execz .LBB0_646
	global_load_ushort v89, v[2:3], off offset:16
.LBB0_646:
	s_or_b64 exec, exec, s[38:39]
	v_lshl_add_u64 v[2:3], s[0:1], 0, v[132:133]
	v_lshl_add_u64 v[4:5], s[28:29], 0, v[132:133]
	global_load_dwordx4 v[50:53], v[2:3], off
	global_load_dwordx4 v[42:45], v[4:5], off
	v_add_lshl_u32 v0, v174, v175, 3
	v_and_b32_e32 v0, 0xfffff000, v0
	v_sub_u32_e32 v0, v120, v0
	v_cmp_lt_i32_e32 vcc, 0, v0
	v_mov_b32_e32 v87, 0
	v_mov_b32_e32 v91, 0
	s_and_saveexec_b64 s[38:39], vcc
	s_cbranch_execz .LBB0_648
	global_load_ushort v91, v[2:3], off offset:-2
.LBB0_648:
	s_or_b64 exec, exec, s[38:39]
	v_cmp_gt_i32_e32 vcc, s6, v0
	s_and_saveexec_b64 s[38:39], vcc
	s_cbranch_execz .LBB0_650
	global_load_ushort v87, v[2:3], off offset:16
.LBB0_650:
	s_or_b64 exec, exec, s[38:39]
	v_lshl_add_u64 v[2:3], s[0:1], 0, v[138:139]
	v_lshl_add_u64 v[4:5], s[28:29], 0, v[138:139]
	global_load_dwordx4 v[38:41], v[2:3], off
	global_load_dwordx4 v[30:33], v[4:5], off
	v_add_lshl_u32 v0, v219, v220, 3
	v_and_b32_e32 v0, 0xfffff000, v0
	v_sub_u32_e32 v0, v124, v0
	v_cmp_lt_i32_e32 vcc, 0, v0
	v_mov_b32_e32 v81, 0
	v_mov_b32_e32 v85, 0
	s_and_saveexec_b64 s[38:39], vcc
	s_cbranch_execz .LBB0_652
	global_load_ushort v85, v[2:3], off offset:-2
.LBB0_652:
	s_or_b64 exec, exec, s[38:39]
	v_cmp_gt_i32_e32 vcc, s6, v0
	s_and_saveexec_b64 s[38:39], vcc
	s_cbranch_execz .LBB0_654
	global_load_ushort v81, v[2:3], off offset:16
.LBB0_654:
	s_or_b64 exec, exec, s[38:39]
	v_lshl_add_u64 v[2:3], s[0:1], 0, v[140:141]
	v_lshl_add_u64 v[4:5], s[28:29], 0, v[140:141]
	global_load_dwordx4 v[34:37], v[2:3], off
	global_load_dwordx4 v[26:29], v[4:5], off
	v_add_lshl_u32 v0, v224, v225, 3
	v_and_b32_e32 v0, 0xfffff000, v0
	v_sub_u32_e32 v0, v128, v0
	v_cmp_lt_i32_e32 vcc, 0, v0
	v_mov_b32_e32 v79, 0
	v_mov_b32_e32 v83, 0
	s_and_saveexec_b64 s[38:39], vcc
	s_cbranch_execz .LBB0_656
	global_load_ushort v83, v[2:3], off offset:-2
.LBB0_656:
	s_or_b64 exec, exec, s[38:39]
	v_cmp_gt_i32_e32 vcc, s6, v0
	s_and_saveexec_b64 s[38:39], vcc
	s_cbranch_execz .LBB0_658
	global_load_ushort v79, v[2:3], off offset:16
.LBB0_658:
	s_or_b64 exec, exec, s[38:39]
	v_lshl_add_u64 v[2:3], s[0:1], 0, v[142:143]
	v_lshl_add_u64 v[4:5], s[28:29], 0, v[142:143]
	global_load_dwordx4 v[22:25], v[2:3], off
	global_load_dwordx4 v[14:17], v[4:5], off
	v_add_lshl_u32 v0, v227, v228, 3
	v_and_b32_e32 v0, 0xfffff000, v0
	v_sub_u32_e32 v0, v130, v0
	v_cmp_lt_i32_e32 vcc, 0, v0
	v_mov_b32_e32 v73, 0
	v_mov_b32_e32 v77, 0
	s_and_saveexec_b64 s[38:39], vcc
	s_cbranch_execz .LBB0_660
	global_load_ushort v77, v[2:3], off offset:-2
.LBB0_660:
	s_or_b64 exec, exec, s[38:39]
	v_cmp_gt_i32_e32 vcc, s6, v0
	s_and_saveexec_b64 s[38:39], vcc
	s_cbranch_execz .LBB0_662
	global_load_ushort v73, v[2:3], off offset:16
.LBB0_662:
	s_or_b64 exec, exec, s[38:39]
	v_lshl_add_u64 v[2:3], s[0:1], 0, v[144:145]
	v_lshl_add_u64 v[4:5], s[28:29], 0, v[144:145]
	global_load_dwordx4 v[18:21], v[2:3], off
	global_load_dwordx4 v[10:13], v[4:5], off
	v_add_lshl_u32 v0, v229, v230, 3
	v_and_b32_e32 v0, 0xfffff000, v0
	v_sub_u32_e32 v0, v134, v0
	v_cmp_lt_i32_e32 vcc, 0, v0
	v_mov_b32_e32 v71, 0
	v_mov_b32_e32 v75, 0
	s_and_saveexec_b64 s[38:39], vcc
	s_cbranch_execz .LBB0_664
	global_load_ushort v75, v[2:3], off offset:-2
.LBB0_664:
	s_or_b64 exec, exec, s[38:39]
	v_cmp_gt_i32_e32 vcc, s6, v0
	s_and_saveexec_b64 s[38:39], vcc
	s_cbranch_execz .LBB0_666
	global_load_ushort v71, v[2:3], off offset:16
.LBB0_666:
	s_or_b64 exec, exec, s[38:39]
	v_lshl_add_u64 v[98:99], s[0:1], 0, v[156:157]
	v_lshl_add_u64 v[2:3], s[28:29], 0, v[156:157]
	global_load_dwordx4 v[6:9], v[98:99], off
	v_add_lshl_u32 v0, v231, v232, 3
	global_load_dwordx4 v[2:5], v[2:3], off
	v_and_b32_e32 v0, 0xfffff000, v0
	v_sub_u32_e32 v0, v136, v0
	v_cmp_lt_i32_e32 vcc, 0, v0
	v_mov_b32_e32 v67, 0
	v_mov_b32_e32 v69, 0
	s_and_saveexec_b64 s[0:1], vcc
	s_cbranch_execz .LBB0_668
	global_load_ushort v69, v[98:99], off offset:-2
.LBB0_668:
	s_or_b64 exec, exec, s[0:1]
	s_movk_i32 s0, 0xff8
	v_cmp_gt_i32_e32 vcc, s0, v0
	s_and_saveexec_b64 s[0:1], vcc
	s_cbranch_execz .LBB0_670
	global_load_ushort v67, v[98:99], off offset:16
.LBB0_670:
	s_or_b64 exec, exec, s[0:1]
	v_ashrrev_i32_e32 v68, 4, v161
	v_lshlrev_b32_e32 v68, 1, v68
	v_mul_i32_i24_e32 v66, 0x2200, v160
	v_and_b32_e32 v68, -4, v68
	v_add3_u32 v66, v66, v162, v68
	v_add_u32_e32 v68, 0x4080, v66
	s_barrier
	s_waitcnt vmcnt(0)
	v_lshlrev_b32_e32 v97, 16, v97
	v_lshlrev_b32_e32 v95, 16, v95
	v_lshlrev_b32_e32 v93, 16, v93
	v_lshlrev_b32_e32 v89, 16, v89
	v_lshlrev_b32_e32 v91, 16, v91
	v_lshlrev_b32_e32 v87, 16, v87
	v_lshlrev_b32_e32 v85, 16, v85
	v_lshlrev_b32_e32 v81, 16, v81
	v_lshlrev_b32_e32 v83, 16, v83
	v_lshlrev_b32_e32 v79, 16, v79
	v_lshlrev_b32_e32 v77, 16, v77
	v_lshlrev_b32_e32 v73, 16, v73
	v_lshlrev_b32_e32 v75, 16, v75
	v_lshlrev_b32_e32 v71, 16, v71
	v_lshlrev_b32_e32 v69, 16, v69
	v_lshlrev_b32_e32 v67, 16, v67
	v_lshlrev_b32_e32 v0, 16, v62
	v_and_b32_e32 v98, 0xffff0000, v64
	v_lshlrev_b32_e32 v99, 16, v65
	v_and_b32_e32 v101, 0xffff0000, v65
	v_lshlrev_b32_e32 v103, 16, v64
	v_and_b32_e32 v62, 0xffff0000, v62
	ds_read2_b32 v[64:65], v68 offset1:1
	v_mov_b32_e32 v96, v62
	v_pk_mul_f32 v[96:97], v[112:113], v[96:97]
	v_and_b32_e32 v102, 0xffff0000, v63
	v_lshlrev_b32_e32 v63, 16, v63
	v_pk_fma_f32 v[96:97], v[112:113], v[0:1], v[96:97] op_sel:[0,0,1] op_sel_hi:[1,0,0]
	s_waitcnt lgkmcnt(0)
	v_and_b32_e32 v105, 0xffff0000, v64
	v_pk_fma_f32 v[96:97], v[110:111], v[62:63], v[96:97] op_sel_hi:[0,1,1]
	v_lshlrev_b32_e32 v104, 16, v64
	v_pk_add_f32 v[96:97], v[114:115], v[96:97] op_sel_hi:[0,1]
	v_pk_mul_f32 v[96:97], v[96:97], v[104:105]
	v_pk_mov_b32 v[104:105], v[62:63], v[102:103] op_sel:[1,0]
	v_mov_b32_e32 v0, v113
	v_pk_mul_f32 v[104:105], v[112:113], v[104:105] op_sel_hi:[0,1]
	s_waitcnt vmcnt(14)
	v_and_b32_e32 v107, 0xffff0000, v58
	v_lshlrev_b32_e32 v106, 16, v58
	v_pk_fma_f32 v[62:63], v[0:1], v[62:63], v[104:105] op_sel_hi:[0,1,1]
	v_pk_mul_f32 v[96:97], v[96:97], v[106:107]
	v_pk_fma_f32 v[62:63], v[110:111], v[102:103], v[62:63] op_sel_hi:[0,1,1]
	v_cvt_pk_bf16_f32 v58, v96, v97
	v_and_b32_e32 v97, 0xffff0000, v65
	v_lshlrev_b32_e32 v96, 16, v65
	v_pk_add_f32 v[62:63], v[114:115], v[62:63] op_sel_hi:[0,1]
	v_and_b32_e32 v65, 0xffff0000, v59
	v_lshlrev_b32_e32 v64, 16, v59
	v_pk_mul_f32 v[62:63], v[62:63], v[96:97]
	v_add_u32_e32 v66, 0x4088, v66
	v_pk_mul_f32 v[62:63], v[62:63], v[64:65]
	v_pk_mov_b32 v[104:105], v[102:103], v[98:99] op_sel:[1,0]
	v_cvt_pk_bf16_f32 v59, v62, v63
	ds_read2_b32 v[62:63], v66 offset1:1
	v_pk_mul_f32 v[104:105], v[112:113], v[104:105] op_sel_hi:[0,1]
	v_pk_fma_f32 v[102:103], v[0:1], v[102:103], v[104:105] op_sel_hi:[0,1,1]
	v_pk_fma_f32 v[102:103], v[110:111], v[98:99], v[102:103] op_sel_hi:[0,1,1]
	v_pk_add_f32 v[102:103], v[114:115], v[102:103] op_sel_hi:[0,1]
	s_waitcnt lgkmcnt(0)
	v_and_b32_e32 v65, 0xffff0000, v62
	v_lshlrev_b32_e32 v64, 16, v62
	v_and_b32_e32 v97, 0xffff0000, v60
	v_lshlrev_b32_e32 v96, 16, v60
	v_pk_mul_f32 v[64:65], v[102:103], v[64:65]
	v_mov_b32_e32 v100, v99
	v_pk_mul_f32 v[64:65], v[64:65], v[96:97]
	v_mov_b32_e32 v94, v101
	v_cvt_pk_bf16_f32 v60, v64, v65
	v_pk_mul_f32 v[64:65], v[112:113], v[100:101] op_sel_hi:[0,1]
	v_pk_fma_f32 v[64:65], v[0:1], v[98:99], v[64:65] op_sel_hi:[0,1,1]
	v_pk_fma_f32 v[64:65], v[110:111], v[94:95], v[64:65] op_sel_hi:[0,1,1]
	v_pk_add_f32 v[64:65], v[114:115], v[64:65] op_sel_hi:[0,1]
	v_and_b32_e32 v95, 0xffff0000, v63
	v_lshlrev_b32_e32 v94, 16, v63
	s_add_u32 s0, s4, 0x9004000
	v_pk_mul_f32 v[62:63], v[64:65], v[94:95]
	v_and_b32_e32 v65, 0xffff0000, v61
	v_lshlrev_b32_e32 v64, 16, v61
	s_addc_u32 s1, s5, 0
	v_pk_mul_f32 v[62:63], v[62:63], v[64:65]
	s_waitcnt vmcnt(13)
	v_lshlrev_b32_e32 v64, 16, v54
	v_cvt_pk_bf16_f32 v61, v62, v63
	v_lshl_add_u64 v[62:63], v[118:119], 1, s[0:1]
	global_store_dwordx4 v[62:63], v[58:61], off
	v_lshlrev_b32_e32 v63, 16, v56
	v_and_b32_e32 v54, 0xffff0000, v54
	v_ashrrev_i32_e32 v59, 4, v158
	v_lshlrev_b32_e32 v59, 1, v59
	v_mul_i32_i24_e32 v58, 0x2200, v155
	v_and_b32_e32 v59, -4, v59
	v_add3_u32 v58, v58, v167, v59
	v_add_u32_e32 v65, 0x4080, v58
	v_add_u32_e32 v66, 0x4088, v58
	v_and_b32_e32 v58, 0xffff0000, v56
	v_lshlrev_b32_e32 v59, 16, v57
	v_and_b32_e32 v61, 0xffff0000, v57
	ds_read2_b32 v[56:57], v65 offset1:1
	v_mov_b32_e32 v92, v54
	v_pk_mul_f32 v[92:93], v[112:113], v[92:93]
	v_and_b32_e32 v62, 0xffff0000, v55
	v_lshlrev_b32_e32 v55, 16, v55
	v_pk_fma_f32 v[64:65], v[112:113], v[64:65], v[92:93] op_sel:[0,0,1] op_sel_hi:[1,0,0]
	v_pk_mov_b32 v[92:93], v[54:55], v[62:63] op_sel:[1,0]
	v_pk_fma_f32 v[64:65], v[110:111], v[54:55], v[64:65] op_sel_hi:[0,1,1]
	s_waitcnt lgkmcnt(0)
	v_and_b32_e32 v95, 0xffff0000, v56
	v_lshlrev_b32_e32 v94, 16, v56
	v_pk_add_f32 v[64:65], v[114:115], v[64:65] op_sel_hi:[0,1]
	v_pk_mul_f32 v[92:93], v[112:113], v[92:93] op_sel_hi:[0,1]
	s_waitcnt vmcnt(13)
	v_and_b32_e32 v97, 0xffff0000, v46
	v_lshlrev_b32_e32 v96, 16, v46
	v_pk_mul_f32 v[64:65], v[64:65], v[94:95]
	v_pk_fma_f32 v[54:55], v[0:1], v[54:55], v[92:93] op_sel_hi:[0,1,1]
	v_pk_mul_f32 v[64:65], v[64:65], v[96:97]
	v_pk_fma_f32 v[54:55], v[110:111], v[62:63], v[54:55] op_sel_hi:[0,1,1]
	v_cvt_pk_bf16_f32 v46, v64, v65
	v_and_b32_e32 v65, 0xffff0000, v57
	v_lshlrev_b32_e32 v64, 16, v57
	v_pk_add_f32 v[54:55], v[114:115], v[54:55] op_sel_hi:[0,1]
	v_and_b32_e32 v57, 0xffff0000, v47
	v_lshlrev_b32_e32 v56, 16, v47
	v_pk_mul_f32 v[54:55], v[54:55], v[64:65]
	v_pk_mov_b32 v[92:93], v[62:63], v[58:59] op_sel:[1,0]
	v_pk_mul_f32 v[54:55], v[54:55], v[56:57]
	v_pk_mul_f32 v[92:93], v[112:113], v[92:93] op_sel_hi:[0,1]
	v_cvt_pk_bf16_f32 v47, v54, v55
	ds_read2_b32 v[54:55], v66 offset1:1
	v_pk_fma_f32 v[62:63], v[0:1], v[62:63], v[92:93] op_sel_hi:[0,1,1]
	v_pk_fma_f32 v[62:63], v[110:111], v[58:59], v[62:63] op_sel_hi:[0,1,1]
	v_pk_add_f32 v[62:63], v[114:115], v[62:63] op_sel_hi:[0,1]
	v_and_b32_e32 v65, 0xffff0000, v48
	s_waitcnt lgkmcnt(0)
	v_and_b32_e32 v57, 0xffff0000, v54
	v_lshlrev_b32_e32 v56, 16, v54
	v_lshlrev_b32_e32 v64, 16, v48
	v_pk_mul_f32 v[56:57], v[62:63], v[56:57]
	v_mov_b32_e32 v60, v59
	v_pk_mul_f32 v[56:57], v[56:57], v[64:65]
	v_mov_b32_e32 v88, v61
	v_cvt_pk_bf16_f32 v48, v56, v57
	v_pk_mul_f32 v[56:57], v[112:113], v[60:61] op_sel_hi:[0,1]
	v_pk_fma_f32 v[56:57], v[0:1], v[58:59], v[56:57] op_sel_hi:[0,1,1]
	v_pk_fma_f32 v[56:57], v[110:111], v[88:89], v[56:57] op_sel_hi:[0,1,1]
	v_pk_add_f32 v[56:57], v[114:115], v[56:57] op_sel_hi:[0,1]
	v_and_b32_e32 v59, 0xffff0000, v55
	v_lshlrev_b32_e32 v58, 16, v55
	v_pk_mul_f32 v[54:55], v[56:57], v[58:59]
	v_and_b32_e32 v57, 0xffff0000, v49
	v_lshlrev_b32_e32 v56, 16, v49
	v_pk_mul_f32 v[54:55], v[54:55], v[56:57]
	s_waitcnt vmcnt(12)
	v_lshlrev_b32_e32 v57, 16, v52
	v_cvt_pk_bf16_f32 v49, v54, v55
	v_lshl_add_u64 v[54:55], v[116:117], 1, s[0:1]
	global_store_dwordx4 v[54:55], v[46:49], off
	v_and_b32_e32 v55, 0xffff0000, v53
	v_and_b32_e32 v56, 0xffff0000, v51
	v_ashrrev_i32_e32 v48, 4, v165
	v_lshlrev_b32_e32 v48, 1, v48
	v_mul_i32_i24_e32 v47, 0x2200, v163
	v_and_b32_e32 v48, -4, v48
	v_add3_u32 v47, v47, v168, v48
	v_add_u32_e32 v58, 0x4080, v47
	v_lshlrev_b32_e32 v46, 16, v50
	v_and_b32_e32 v48, 0xffff0000, v52
	v_lshlrev_b32_e32 v49, 16, v53
	v_and_b32_e32 v50, 0xffff0000, v50
	ds_read2_b32 v[52:53], v58 offset1:1
	v_mov_b32_e32 v90, v50
	v_pk_mul_f32 v[62:63], v[112:113], v[90:91]
	v_add_u32_e32 v64, 0x4088, v47
	v_lshlrev_b32_e32 v51, 16, v51
	v_pk_fma_f32 v[46:47], v[112:113], v[46:47], v[62:63] op_sel:[0,0,1] op_sel_hi:[1,0,0]
	s_waitcnt lgkmcnt(0)
	v_and_b32_e32 v59, 0xffff0000, v52
	v_pk_fma_f32 v[46:47], v[110:111], v[50:51], v[46:47] op_sel_hi:[0,1,1]
	v_lshlrev_b32_e32 v58, 16, v52
	v_pk_add_f32 v[46:47], v[114:115], v[46:47] op_sel_hi:[0,1]
	v_pk_mul_f32 v[46:47], v[46:47], v[58:59]
	v_pk_mov_b32 v[58:59], v[50:51], v[56:57] op_sel:[1,0]
	s_waitcnt vmcnt(12)
	v_and_b32_e32 v61, 0xffff0000, v42
	v_pk_mul_f32 v[58:59], v[112:113], v[58:59] op_sel_hi:[0,1]
	v_lshlrev_b32_e32 v60, 16, v42
	v_pk_fma_f32 v[50:51], v[0:1], v[50:51], v[58:59] op_sel_hi:[0,1,1]
	v_pk_mul_f32 v[46:47], v[46:47], v[60:61]
	v_pk_fma_f32 v[50:51], v[110:111], v[56:57], v[50:51] op_sel_hi:[0,1,1]
	v_cvt_pk_bf16_f32 v42, v46, v47
	v_and_b32_e32 v47, 0xffff0000, v53
	v_lshlrev_b32_e32 v46, 16, v53
	v_pk_add_f32 v[50:51], v[114:115], v[50:51] op_sel_hi:[0,1]
	v_and_b32_e32 v53, 0xffff0000, v43
	v_lshlrev_b32_e32 v52, 16, v43
	v_pk_mul_f32 v[46:47], v[50:51], v[46:47]
	v_pk_mov_b32 v[58:59], v[56:57], v[48:49] op_sel:[1,0]
	v_pk_mul_f32 v[46:47], v[46:47], v[52:53]
	v_pk_mul_f32 v[58:59], v[112:113], v[58:59] op_sel_hi:[0,1]
	v_cvt_pk_bf16_f32 v43, v46, v47
	ds_read2_b32 v[46:47], v64 offset1:1
	v_pk_fma_f32 v[56:57], v[0:1], v[56:57], v[58:59] op_sel_hi:[0,1,1]
	v_pk_fma_f32 v[56:57], v[110:111], v[48:49], v[56:57] op_sel_hi:[0,1,1]
	v_pk_add_f32 v[56:57], v[114:115], v[56:57] op_sel_hi:[0,1]
	v_and_b32_e32 v53, 0xffff0000, v44
	s_waitcnt lgkmcnt(0)
	v_and_b32_e32 v51, 0xffff0000, v46
	v_lshlrev_b32_e32 v50, 16, v46
	v_lshlrev_b32_e32 v52, 16, v44
	v_pk_mul_f32 v[50:51], v[56:57], v[50:51]
	v_mov_b32_e32 v54, v49
	v_pk_mul_f32 v[50:51], v[50:51], v[52:53]
	v_mov_b32_e32 v86, v55
	v_cvt_pk_bf16_f32 v44, v50, v51
	v_pk_mul_f32 v[50:51], v[112:113], v[54:55] op_sel_hi:[0,1]
	v_pk_fma_f32 v[48:49], v[0:1], v[48:49], v[50:51] op_sel_hi:[0,1,1]
	v_pk_fma_f32 v[48:49], v[110:111], v[86:87], v[48:49] op_sel_hi:[0,1,1]
	v_pk_add_f32 v[48:49], v[114:115], v[48:49] op_sel_hi:[0,1]
	v_and_b32_e32 v51, 0xffff0000, v47
	v_lshlrev_b32_e32 v50, 16, v47
	v_pk_mul_f32 v[46:47], v[48:49], v[50:51]
	v_and_b32_e32 v49, 0xffff0000, v45
	v_lshlrev_b32_e32 v48, 16, v45
	v_pk_mul_f32 v[46:47], v[46:47], v[48:49]
	s_waitcnt vmcnt(11)
	v_lshlrev_b32_e32 v48, 16, v38
	v_cvt_pk_bf16_f32 v45, v46, v47
	v_lshl_add_u64 v[46:47], v[120:121], 1, s[0:1]
	global_store_dwordx4 v[46:47], v[42:45], off
	v_lshlrev_b32_e32 v47, 16, v40
	v_and_b32_e32 v38, 0xffff0000, v38
	v_ashrrev_i32_e32 v43, 4, v170
	v_lshlrev_b32_e32 v43, 1, v43
	v_mul_i32_i24_e32 v42, 0x2200, v169
	v_and_b32_e32 v43, -4, v43
	v_add3_u32 v42, v42, v173, v43
	v_add_u32_e32 v49, 0x4080, v42
	v_add_u32_e32 v56, 0x4088, v42
	v_and_b32_e32 v42, 0xffff0000, v40
	v_lshlrev_b32_e32 v43, 16, v41
	v_and_b32_e32 v45, 0xffff0000, v41
	ds_read2_b32 v[40:41], v49 offset1:1
	v_mov_b32_e32 v84, v38
	v_pk_mul_f32 v[54:55], v[112:113], v[84:85]
	v_and_b32_e32 v46, 0xffff0000, v39
	v_lshlrev_b32_e32 v39, 16, v39
	v_pk_fma_f32 v[48:49], v[112:113], v[48:49], v[54:55] op_sel:[0,0,1] op_sel_hi:[1,0,0]
	s_waitcnt lgkmcnt(0)
	v_and_b32_e32 v51, 0xffff0000, v40
	v_pk_fma_f32 v[48:49], v[110:111], v[38:39], v[48:49] op_sel_hi:[0,1,1]
	v_lshlrev_b32_e32 v50, 16, v40
	v_pk_add_f32 v[48:49], v[114:115], v[48:49] op_sel_hi:[0,1]
	v_pk_mul_f32 v[48:49], v[48:49], v[50:51]
	v_pk_mov_b32 v[50:51], v[38:39], v[46:47] op_sel:[1,0]
	s_waitcnt vmcnt(11)
	v_and_b32_e32 v53, 0xffff0000, v30
	v_pk_mul_f32 v[50:51], v[112:113], v[50:51] op_sel_hi:[0,1]
	v_lshlrev_b32_e32 v52, 16, v30
	v_pk_fma_f32 v[38:39], v[0:1], v[38:39], v[50:51] op_sel_hi:[0,1,1]
	v_pk_mul_f32 v[48:49], v[48:49], v[52:53]
	v_pk_fma_f32 v[38:39], v[110:111], v[46:47], v[38:39] op_sel_hi:[0,1,1]
	v_cvt_pk_bf16_f32 v30, v48, v49
	v_and_b32_e32 v49, 0xffff0000, v41
	v_lshlrev_b32_e32 v48, 16, v41
	v_pk_add_f32 v[38:39], v[114:115], v[38:39] op_sel_hi:[0,1]
	v_and_b32_e32 v41, 0xffff0000, v31
	v_lshlrev_b32_e32 v40, 16, v31
	v_pk_mul_f32 v[38:39], v[38:39], v[48:49]
	v_pk_mov_b32 v[50:51], v[46:47], v[42:43] op_sel:[1,0]
	v_pk_mul_f32 v[38:39], v[38:39], v[40:41]
	v_pk_mul_f32 v[50:51], v[112:113], v[50:51] op_sel_hi:[0,1]
	v_cvt_pk_bf16_f32 v31, v38, v39
	ds_read2_b32 v[38:39], v56 offset1:1
	v_pk_fma_f32 v[46:47], v[0:1], v[46:47], v[50:51] op_sel_hi:[0,1,1]
	v_pk_fma_f32 v[46:47], v[110:111], v[42:43], v[46:47] op_sel_hi:[0,1,1]
	v_pk_add_f32 v[46:47], v[114:115], v[46:47] op_sel_hi:[0,1]
	v_and_b32_e32 v49, 0xffff0000, v32
	s_waitcnt lgkmcnt(0)
	v_and_b32_e32 v41, 0xffff0000, v38
	v_lshlrev_b32_e32 v40, 16, v38
	v_lshlrev_b32_e32 v48, 16, v32
	v_pk_mul_f32 v[40:41], v[46:47], v[40:41]
	v_mov_b32_e32 v44, v43
	v_pk_mul_f32 v[40:41], v[40:41], v[48:49]
	v_mov_b32_e32 v80, v45
	v_cvt_pk_bf16_f32 v32, v40, v41
	v_pk_mul_f32 v[40:41], v[112:113], v[44:45] op_sel_hi:[0,1]
	v_pk_fma_f32 v[40:41], v[0:1], v[42:43], v[40:41] op_sel_hi:[0,1,1]
	v_pk_fma_f32 v[40:41], v[110:111], v[80:81], v[40:41] op_sel_hi:[0,1,1]
	v_pk_add_f32 v[40:41], v[114:115], v[40:41] op_sel_hi:[0,1]
	v_and_b32_e32 v43, 0xffff0000, v39
	v_lshlrev_b32_e32 v42, 16, v39
	v_pk_mul_f32 v[38:39], v[40:41], v[42:43]
	v_and_b32_e32 v41, 0xffff0000, v33
	v_lshlrev_b32_e32 v40, 16, v33
	v_pk_mul_f32 v[38:39], v[38:39], v[40:41]
	s_waitcnt vmcnt(10)
	v_lshlrev_b32_e32 v41, 16, v36
	v_cvt_pk_bf16_f32 v33, v38, v39
	v_lshl_add_u64 v[38:39], v[124:125], 1, s[0:1]
	global_store_dwordx4 v[38:39], v[30:33], off
	v_and_b32_e32 v39, 0xffff0000, v37
	v_and_b32_e32 v40, 0xffff0000, v35
	v_ashrrev_i32_e32 v32, 4, v172
	v_lshlrev_b32_e32 v32, 1, v32
	v_mul_i32_i24_e32 v31, 0x2200, v171
	v_and_b32_e32 v32, -4, v32
	v_add3_u32 v31, v31, v176, v32
	v_add_u32_e32 v42, 0x4080, v31
	v_lshlrev_b32_e32 v30, 16, v34
	v_and_b32_e32 v32, 0xffff0000, v36
	v_lshlrev_b32_e32 v33, 16, v37
	v_and_b32_e32 v34, 0xffff0000, v34
	ds_read2_b32 v[36:37], v42 offset1:1
	v_mov_b32_e32 v82, v34
	v_pk_mul_f32 v[46:47], v[112:113], v[82:83]
	v_add_u32_e32 v48, 0x4088, v31
	v_lshlrev_b32_e32 v35, 16, v35
	v_pk_fma_f32 v[30:31], v[112:113], v[30:31], v[46:47] op_sel:[0,0,1] op_sel_hi:[1,0,0]
	s_waitcnt lgkmcnt(0)
	v_and_b32_e32 v43, 0xffff0000, v36
	v_pk_fma_f32 v[30:31], v[110:111], v[34:35], v[30:31] op_sel_hi:[0,1,1]
	v_lshlrev_b32_e32 v42, 16, v36
	v_pk_add_f32 v[30:31], v[114:115], v[30:31] op_sel_hi:[0,1]
	v_pk_mul_f32 v[30:31], v[30:31], v[42:43]
	v_pk_mov_b32 v[42:43], v[34:35], v[40:41] op_sel:[1,0]
	s_waitcnt vmcnt(10)
	v_and_b32_e32 v45, 0xffff0000, v26
	v_pk_mul_f32 v[42:43], v[112:113], v[42:43] op_sel_hi:[0,1]
	v_lshlrev_b32_e32 v44, 16, v26
	v_pk_fma_f32 v[34:35], v[0:1], v[34:35], v[42:43] op_sel_hi:[0,1,1]
	v_pk_mul_f32 v[30:31], v[30:31], v[44:45]
	v_pk_fma_f32 v[34:35], v[110:111], v[40:41], v[34:35] op_sel_hi:[0,1,1]
	v_cvt_pk_bf16_f32 v26, v30, v31
	v_and_b32_e32 v31, 0xffff0000, v37
	v_lshlrev_b32_e32 v30, 16, v37
	v_pk_add_f32 v[34:35], v[114:115], v[34:35] op_sel_hi:[0,1]
	v_and_b32_e32 v37, 0xffff0000, v27
	v_lshlrev_b32_e32 v36, 16, v27
	v_pk_mul_f32 v[30:31], v[34:35], v[30:31]
	v_pk_mov_b32 v[42:43], v[40:41], v[32:33] op_sel:[1,0]
	v_pk_mul_f32 v[30:31], v[30:31], v[36:37]
	v_pk_mul_f32 v[42:43], v[112:113], v[42:43] op_sel_hi:[0,1]
	v_cvt_pk_bf16_f32 v27, v30, v31
	ds_read2_b32 v[30:31], v48 offset1:1
	v_pk_fma_f32 v[40:41], v[0:1], v[40:41], v[42:43] op_sel_hi:[0,1,1]
	v_pk_fma_f32 v[40:41], v[110:111], v[32:33], v[40:41] op_sel_hi:[0,1,1]
	v_pk_add_f32 v[40:41], v[114:115], v[40:41] op_sel_hi:[0,1]
	v_and_b32_e32 v37, 0xffff0000, v28
	s_waitcnt lgkmcnt(0)
	v_and_b32_e32 v35, 0xffff0000, v30
	v_lshlrev_b32_e32 v34, 16, v30
	v_lshlrev_b32_e32 v36, 16, v28
	v_pk_mul_f32 v[34:35], v[40:41], v[34:35]
	v_mov_b32_e32 v38, v33
	v_pk_mul_f32 v[34:35], v[34:35], v[36:37]
	v_mov_b32_e32 v78, v39
	v_cvt_pk_bf16_f32 v28, v34, v35
	v_pk_mul_f32 v[34:35], v[112:113], v[38:39] op_sel_hi:[0,1]
	v_pk_fma_f32 v[32:33], v[0:1], v[32:33], v[34:35] op_sel_hi:[0,1,1]
	v_pk_fma_f32 v[32:33], v[110:111], v[78:79], v[32:33] op_sel_hi:[0,1,1]
	v_pk_add_f32 v[32:33], v[114:115], v[32:33] op_sel_hi:[0,1]
	v_and_b32_e32 v35, 0xffff0000, v31
	v_lshlrev_b32_e32 v34, 16, v31
	v_pk_mul_f32 v[30:31], v[32:33], v[34:35]
	v_and_b32_e32 v33, 0xffff0000, v29
	v_lshlrev_b32_e32 v32, 16, v29
	v_pk_mul_f32 v[30:31], v[30:31], v[32:33]
	s_waitcnt vmcnt(9)
	v_lshlrev_b32_e32 v32, 16, v22
	v_cvt_pk_bf16_f32 v29, v30, v31
	v_lshl_add_u64 v[30:31], v[128:129], 1, s[0:1]
	global_store_dwordx4 v[30:31], v[26:29], off
	v_lshlrev_b32_e32 v31, 16, v24
	v_and_b32_e32 v22, 0xffff0000, v22
	v_ashrrev_i32_e32 v27, 4, v178
	v_lshlrev_b32_e32 v27, 1, v27
	v_mul_i32_i24_e32 v26, 0x2200, v177
	v_and_b32_e32 v27, -4, v27
	v_add3_u32 v26, v26, v218, v27
	v_add_u32_e32 v33, 0x4080, v26
	v_add_u32_e32 v40, 0x4088, v26
	v_and_b32_e32 v26, 0xffff0000, v24
	v_lshlrev_b32_e32 v27, 16, v25
	v_and_b32_e32 v29, 0xffff0000, v25
	ds_read2_b32 v[24:25], v33 offset1:1
	v_mov_b32_e32 v76, v22
	v_pk_mul_f32 v[38:39], v[112:113], v[76:77]
	v_and_b32_e32 v30, 0xffff0000, v23
	v_lshlrev_b32_e32 v23, 16, v23
	v_pk_fma_f32 v[32:33], v[112:113], v[32:33], v[38:39] op_sel:[0,0,1] op_sel_hi:[1,0,0]
	s_waitcnt lgkmcnt(0)
	v_and_b32_e32 v35, 0xffff0000, v24
	v_pk_fma_f32 v[32:33], v[110:111], v[22:23], v[32:33] op_sel_hi:[0,1,1]
	v_lshlrev_b32_e32 v34, 16, v24
	v_pk_add_f32 v[32:33], v[114:115], v[32:33] op_sel_hi:[0,1]
	v_pk_mul_f32 v[32:33], v[32:33], v[34:35]
	v_pk_mov_b32 v[34:35], v[22:23], v[30:31] op_sel:[1,0]
	s_waitcnt vmcnt(9)
	v_and_b32_e32 v37, 0xffff0000, v14
	v_pk_mul_f32 v[34:35], v[112:113], v[34:35] op_sel_hi:[0,1]
	v_lshlrev_b32_e32 v36, 16, v14
	v_pk_fma_f32 v[22:23], v[0:1], v[22:23], v[34:35] op_sel_hi:[0,1,1]
	v_pk_mul_f32 v[32:33], v[32:33], v[36:37]
	v_pk_fma_f32 v[22:23], v[110:111], v[30:31], v[22:23] op_sel_hi:[0,1,1]
	v_cvt_pk_bf16_f32 v14, v32, v33
	v_and_b32_e32 v33, 0xffff0000, v25
	v_lshlrev_b32_e32 v32, 16, v25
	v_pk_add_f32 v[22:23], v[114:115], v[22:23] op_sel_hi:[0,1]
	v_and_b32_e32 v25, 0xffff0000, v15
	v_lshlrev_b32_e32 v24, 16, v15
	v_pk_mul_f32 v[22:23], v[22:23], v[32:33]
	v_pk_mov_b32 v[34:35], v[30:31], v[26:27] op_sel:[1,0]
	v_pk_mul_f32 v[22:23], v[22:23], v[24:25]
	v_pk_mul_f32 v[34:35], v[112:113], v[34:35] op_sel_hi:[0,1]
	v_cvt_pk_bf16_f32 v15, v22, v23
	ds_read2_b32 v[22:23], v40 offset1:1
	v_pk_fma_f32 v[30:31], v[0:1], v[30:31], v[34:35] op_sel_hi:[0,1,1]
	v_pk_fma_f32 v[30:31], v[110:111], v[26:27], v[30:31] op_sel_hi:[0,1,1]
	v_pk_add_f32 v[30:31], v[114:115], v[30:31] op_sel_hi:[0,1]
	v_and_b32_e32 v33, 0xffff0000, v16
	s_waitcnt lgkmcnt(0)
	v_and_b32_e32 v25, 0xffff0000, v22
	v_lshlrev_b32_e32 v24, 16, v22
	v_lshlrev_b32_e32 v32, 16, v16
	v_pk_mul_f32 v[24:25], v[30:31], v[24:25]
	v_mov_b32_e32 v28, v27
	v_pk_mul_f32 v[24:25], v[24:25], v[32:33]
	v_mov_b32_e32 v72, v29
	v_cvt_pk_bf16_f32 v16, v24, v25
	v_pk_mul_f32 v[24:25], v[112:113], v[28:29] op_sel_hi:[0,1]
	v_pk_fma_f32 v[24:25], v[0:1], v[26:27], v[24:25] op_sel_hi:[0,1,1]
	v_pk_fma_f32 v[24:25], v[110:111], v[72:73], v[24:25] op_sel_hi:[0,1,1]
	v_pk_add_f32 v[24:25], v[114:115], v[24:25] op_sel_hi:[0,1]
	v_and_b32_e32 v27, 0xffff0000, v23
	v_lshlrev_b32_e32 v26, 16, v23
	v_pk_mul_f32 v[22:23], v[24:25], v[26:27]
	v_and_b32_e32 v25, 0xffff0000, v17
	v_lshlrev_b32_e32 v24, 16, v17
	v_pk_mul_f32 v[22:23], v[22:23], v[24:25]
	s_waitcnt vmcnt(8)
	v_lshlrev_b32_e32 v25, 16, v20
	v_cvt_pk_bf16_f32 v17, v22, v23
	v_lshl_add_u64 v[22:23], v[130:131], 1, s[0:1]
	global_store_dwordx4 v[22:23], v[14:17], off
	v_and_b32_e32 v23, 0xffff0000, v21
	v_and_b32_e32 v24, 0xffff0000, v19
	v_ashrrev_i32_e32 v16, 4, v181
	v_lshlrev_b32_e32 v16, 1, v16
	v_mul_i32_i24_e32 v15, 0x2200, v180
	v_and_b32_e32 v16, -4, v16
	v_add3_u32 v15, v15, v221, v16
	v_add_u32_e32 v26, 0x4080, v15
	v_lshlrev_b32_e32 v14, 16, v18
	v_and_b32_e32 v16, 0xffff0000, v20
	v_lshlrev_b32_e32 v17, 16, v21
	v_and_b32_e32 v18, 0xffff0000, v18
	ds_read2_b32 v[20:21], v26 offset1:1
	v_mov_b32_e32 v74, v18
	v_pk_mul_f32 v[30:31], v[112:113], v[74:75]
	v_add_u32_e32 v32, 0x4088, v15
	v_lshlrev_b32_e32 v19, 16, v19
	v_pk_fma_f32 v[14:15], v[112:113], v[14:15], v[30:31] op_sel:[0,0,1] op_sel_hi:[1,0,0]
	s_waitcnt lgkmcnt(0)
	v_and_b32_e32 v27, 0xffff0000, v20
	v_pk_fma_f32 v[14:15], v[110:111], v[18:19], v[14:15] op_sel_hi:[0,1,1]
	v_lshlrev_b32_e32 v26, 16, v20
	v_pk_add_f32 v[14:15], v[114:115], v[14:15] op_sel_hi:[0,1]
	v_pk_mul_f32 v[14:15], v[14:15], v[26:27]
	v_pk_mov_b32 v[26:27], v[18:19], v[24:25] op_sel:[1,0]
	s_waitcnt vmcnt(8)
	v_and_b32_e32 v29, 0xffff0000, v10
	v_pk_mul_f32 v[26:27], v[112:113], v[26:27] op_sel_hi:[0,1]
	v_lshlrev_b32_e32 v28, 16, v10
	v_pk_fma_f32 v[18:19], v[0:1], v[18:19], v[26:27] op_sel_hi:[0,1,1]
	v_pk_mul_f32 v[14:15], v[14:15], v[28:29]
	v_pk_fma_f32 v[18:19], v[110:111], v[24:25], v[18:19] op_sel_hi:[0,1,1]
	v_cvt_pk_bf16_f32 v10, v14, v15
	v_and_b32_e32 v15, 0xffff0000, v21
	v_lshlrev_b32_e32 v14, 16, v21
	v_pk_add_f32 v[18:19], v[114:115], v[18:19] op_sel_hi:[0,1]
	v_and_b32_e32 v21, 0xffff0000, v11
	v_lshlrev_b32_e32 v20, 16, v11
	v_pk_mul_f32 v[14:15], v[18:19], v[14:15]
	v_pk_mov_b32 v[26:27], v[24:25], v[16:17] op_sel:[1,0]
	v_pk_mul_f32 v[14:15], v[14:15], v[20:21]
	v_pk_mul_f32 v[26:27], v[112:113], v[26:27] op_sel_hi:[0,1]
	v_cvt_pk_bf16_f32 v11, v14, v15
	ds_read2_b32 v[14:15], v32 offset1:1
	v_pk_fma_f32 v[24:25], v[0:1], v[24:25], v[26:27] op_sel_hi:[0,1,1]
	v_pk_fma_f32 v[24:25], v[110:111], v[16:17], v[24:25] op_sel_hi:[0,1,1]
	v_pk_add_f32 v[24:25], v[114:115], v[24:25] op_sel_hi:[0,1]
	v_and_b32_e32 v21, 0xffff0000, v12
	s_waitcnt lgkmcnt(0)
	v_and_b32_e32 v19, 0xffff0000, v14
	v_lshlrev_b32_e32 v18, 16, v14
	v_lshlrev_b32_e32 v20, 16, v12
	v_pk_mul_f32 v[18:19], v[24:25], v[18:19]
	v_mov_b32_e32 v22, v17
	v_pk_mul_f32 v[18:19], v[18:19], v[20:21]
	v_mov_b32_e32 v70, v23
	v_cvt_pk_bf16_f32 v12, v18, v19
	v_pk_mul_f32 v[18:19], v[112:113], v[22:23] op_sel_hi:[0,1]
	v_pk_fma_f32 v[16:17], v[0:1], v[16:17], v[18:19] op_sel_hi:[0,1,1]
	v_pk_fma_f32 v[16:17], v[110:111], v[70:71], v[16:17] op_sel_hi:[0,1,1]
	v_pk_add_f32 v[16:17], v[114:115], v[16:17] op_sel_hi:[0,1]
	v_and_b32_e32 v19, 0xffff0000, v15
	v_lshlrev_b32_e32 v18, 16, v15
	v_pk_mul_f32 v[14:15], v[16:17], v[18:19]
	v_and_b32_e32 v17, 0xffff0000, v13
	v_lshlrev_b32_e32 v16, 16, v13
	v_pk_mul_f32 v[14:15], v[14:15], v[16:17]
	s_waitcnt vmcnt(7)
	v_lshlrev_b32_e32 v16, 16, v6
	v_cvt_pk_bf16_f32 v13, v14, v15
	v_lshl_add_u64 v[14:15], v[134:135], 1, s[0:1]
	global_store_dwordx4 v[14:15], v[10:13], off
	v_lshlrev_b32_e32 v15, 16, v8
	v_and_b32_e32 v6, 0xffff0000, v6
	v_ashrrev_i32_e32 v11, 4, v223
	v_lshlrev_b32_e32 v11, 1, v11
	v_mul_i32_i24_e32 v10, 0x2200, v222
	v_and_b32_e32 v11, -4, v11
	v_add3_u32 v10, v10, v226, v11
	v_add_u32_e32 v17, 0x4080, v10
	v_add_u32_e32 v24, 0x4088, v10
	v_and_b32_e32 v10, 0xffff0000, v8
	v_lshlrev_b32_e32 v11, 16, v9
	v_and_b32_e32 v13, 0xffff0000, v9
	ds_read2_b32 v[8:9], v17 offset1:1
	v_mov_b32_e32 v68, v6
	v_pk_mul_f32 v[22:23], v[112:113], v[68:69]
	v_and_b32_e32 v14, 0xffff0000, v7
	v_lshlrev_b32_e32 v7, 16, v7
	v_pk_fma_f32 v[16:17], v[112:113], v[16:17], v[22:23] op_sel:[0,0,1] op_sel_hi:[1,0,0]
	s_waitcnt lgkmcnt(0)
	v_and_b32_e32 v19, 0xffff0000, v8
	v_pk_fma_f32 v[16:17], v[110:111], v[6:7], v[16:17] op_sel_hi:[0,1,1]
	v_lshlrev_b32_e32 v18, 16, v8
	v_pk_add_f32 v[16:17], v[114:115], v[16:17] op_sel_hi:[0,1]
	v_pk_mul_f32 v[16:17], v[16:17], v[18:19]
	v_pk_mov_b32 v[18:19], v[6:7], v[14:15] op_sel:[1,0]
	s_waitcnt vmcnt(7)
	v_and_b32_e32 v21, 0xffff0000, v2
	v_pk_mul_f32 v[18:19], v[112:113], v[18:19] op_sel_hi:[0,1]
	v_lshlrev_b32_e32 v20, 16, v2
	v_pk_fma_f32 v[6:7], v[0:1], v[6:7], v[18:19] op_sel_hi:[0,1,1]
	v_pk_mul_f32 v[16:17], v[16:17], v[20:21]
	v_pk_fma_f32 v[6:7], v[110:111], v[14:15], v[6:7] op_sel_hi:[0,1,1]
	v_cvt_pk_bf16_f32 v2, v16, v17
	v_and_b32_e32 v17, 0xffff0000, v9
	v_lshlrev_b32_e32 v16, 16, v9
	v_pk_add_f32 v[6:7], v[114:115], v[6:7] op_sel_hi:[0,1]
	v_and_b32_e32 v9, 0xffff0000, v3
	v_lshlrev_b32_e32 v8, 16, v3
	v_pk_mul_f32 v[6:7], v[6:7], v[16:17]
	v_pk_mov_b32 v[18:19], v[14:15], v[10:11] op_sel:[1,0]
	v_pk_mul_f32 v[6:7], v[6:7], v[8:9]
	v_pk_mul_f32 v[18:19], v[112:113], v[18:19] op_sel_hi:[0,1]
	v_cvt_pk_bf16_f32 v3, v6, v7
	ds_read2_b32 v[6:7], v24 offset1:1
	v_pk_fma_f32 v[14:15], v[0:1], v[14:15], v[18:19] op_sel_hi:[0,1,1]
	v_pk_fma_f32 v[14:15], v[110:111], v[10:11], v[14:15] op_sel_hi:[0,1,1]
	v_pk_add_f32 v[14:15], v[114:115], v[14:15] op_sel_hi:[0,1]
	v_and_b32_e32 v17, 0xffff0000, v4
	s_waitcnt lgkmcnt(0)
	v_and_b32_e32 v9, 0xffff0000, v6
	v_lshlrev_b32_e32 v8, 16, v6
	v_lshlrev_b32_e32 v16, 16, v4
	v_pk_mul_f32 v[8:9], v[14:15], v[8:9]
	v_mov_b32_e32 v12, v11
	v_pk_mul_f32 v[8:9], v[8:9], v[16:17]
	v_mov_b32_e32 v66, v13
	v_cvt_pk_bf16_f32 v4, v8, v9
	v_pk_mul_f32 v[8:9], v[112:113], v[12:13] op_sel_hi:[0,1]
	v_pk_fma_f32 v[8:9], v[0:1], v[10:11], v[8:9] op_sel_hi:[0,1,1]
	v_pk_fma_f32 v[8:9], v[110:111], v[66:67], v[8:9] op_sel_hi:[0,1,1]
	v_pk_add_f32 v[8:9], v[114:115], v[8:9] op_sel_hi:[0,1]
	v_and_b32_e32 v11, 0xffff0000, v7
	v_lshlrev_b32_e32 v10, 16, v7
	v_pk_mul_f32 v[6:7], v[8:9], v[10:11]
	v_and_b32_e32 v9, 0xffff0000, v5
	v_lshlrev_b32_e32 v8, 16, v5
	v_pk_mul_f32 v[6:7], v[6:7], v[8:9]
	s_nop 0
	v_cvt_pk_bf16_f32 v5, v6, v7
	v_lshl_add_u64 v[6:7], v[136:137], 1, s[0:1]
	global_store_dwordx4 v[6:7], v[2:5], off
